# p6 pass 0: mixer-B GEMM of the 16 leftover tiles runs on workgroups 16..31 in parallel with the mixer-C GEMM on 0..15 (flag word hand-off of macc)
# speedup vs baseline: 1.0067x; 1.0067x over previous
; DEVI char* wsp(const Params& P, size_t off) { asm volatile("" : "+s"(off)); return P.ws + off; }
; DEVI int ltid() { int t = threadIdx.x; asm volatile("" : "+v"(t)); return t; }
; DEVI void stage_tile(const bfu* __restrict__ g, int ld, int k0, char* lds, int tid) {
; #pragma unroll
;   for (int i = 0; i < 4; ++i) {
;     int b = tid * 16 + i * 4096;
;     int r = b >> 7, cp = (b >> 4) & 7, gc = cp ^ (r & 7);
;     __builtin_amdgcn_global_load_lds((const unsigned*)(g + (long)r * ld + k0 + gc * 8),
;                                      (unsigned*)(lds + b), 16, 0, 0);
;   }
; }
; DEVI void phase6(const Params& P, int l, int pass, char* smem) {
;   const int tid = ltid();
;   const int ntok = pass ? 8192 : 8448;
;   const int nM = ntok / 128, nN = 8;
;   const bfu* Z = (const bfu*)wsp(P, O_Z);
;   bfu* M = (bfu*)wsp(P, O_CB);
;   for (int id = blockIdx.x; id < nM * nN; id += gridDim.x) {
;     int pm, pn; tile_rc_m(id, nM, nN, pm, pn);
.LBB0_728:
	s_or_b64 exec, exec, s[26:27]
	s_barrier
	v_mov_b32_e32 v91, v93
	s_cmp_eq_u32 s90, 0
	s_movk_i32 s1, 0x210
	s_mov_b64 s[26:27], 0x8582000
	s_cselect_b32 s1, s1, 0x200
	s_mov_b64 s[26:27], 0x17d02000
	s_cmp_ge_i32 s74, s1
	s_cbranch_scc1 .LBB0_743
	v_ashrrev_i32_e32 v0, 3, v91
	v_lshlrev_b32_e32 v101, 4, v91
	v_xor_b32_e32 v4, v0, v91
	v_lshlrev_b32_e32 v4, 3, v4
	v_add_u32_e32 v103, 0x1000, v101
	v_and_b32_e32 v100, 56, v4
	v_ashrrev_i32_e32 v4, 7, v103
	v_xor_b32_e32 v8, v4, v91
	v_lshlrev_b32_e32 v8, 3, v8
	v_add_u32_e32 v105, 0x2000, v101
	v_and_b32_e32 v102, 56, v8
	v_ashrrev_i32_e32 v8, 7, v105
	v_xor_b32_e32 v12, v8, v91
	v_lshrrev_b32_e32 v16, 4, v91
	v_lshlrev_b32_e32 v12, 3, v12
	v_add_u32_e32 v107, 0x3000, v101
	v_and_b32_e32 v20, 7, v91
	v_and_b32_e32 v104, 56, v12
	v_ashrrev_i32_e32 v12, 7, v107
	v_bitop3_b32 v16, v16, v20, 3 bitop3:0x6c
	v_bfe_u32 v17, v91, 4, 2
	v_xor_b32_e32 v18, v12, v91
	v_lshlrev_b32_e32 v146, 4, v16
	v_lshlrev_b32_e32 v16, 7, v91
	v_lshlrev_b32_e32 v18, 3, v18
	v_and_b32_e32 v148, 0x2780, v16
	v_bitop3_b32 v16, v17, v20, 4 bitop3:0x36
	v_and_b32_e32 v106, 56, v18
	v_and_b32_e32 v18, 15, v91
	v_lshrrev_b32_e32 v19, 1, v91
	s_mov_b32 s2, 0x1ffffc0
	v_lshlrev_b32_e32 v149, 4, v16
	v_lshrrev_b32_e32 v16, 2, v91
	v_and_or_b32 v18, v19, s2, v18
	v_and_b32_e32 v16, 12, v16
	s_mov_b32 s2, 0x7fffc0
	v_and_or_b32 v16, v19, s2, v16
	v_and_b32_e32 v17, 0x4f, v91
	v_lshlrev_b32_e32 v16, 9, v16
	v_ashrrev_i32_e32 v1, 31, v0
	v_lshl_or_b32 v150, v17, 2, v16
	v_lshlrev_b32_e32 v16, 2, v91
	v_lshlrev_b64 v[2:3], 10, v[0:1]
	v_ashrrev_i32_e32 v5, 31, v4
	v_and_b32_e32 v151, 0x7c, v16
	v_lshlrev_b64 v[16:17], 11, v[0:1]
	v_bitop3_b32 v0, v0, 7, v91 bitop3:0x48
	v_lshlrev_b64 v[6:7], 10, v[4:5]
	v_lshl_or_b32 v16, v0, 4, v16
	v_readlane_b32 s4, v252, 25
	v_lshlrev_b64 v[0:1], 11, v[4:5]
	v_bitop3_b32 v4, v4, 7, v91 bitop3:0x48
	v_ashrrev_i32_e32 v9, 31, v8
	v_readlane_b32 s5, v252, 26
	v_lshl_or_b32 v0, v4, 4, v0
	v_bitop3_b32 v4, v8, 7, v91 bitop3:0x48
	v_lshl_add_u64 v[110:111], s[4:5], 0, v[0:1]
	v_lshlrev_b64 v[0:1], 11, v[8:9]
	v_ashrrev_i32_e32 v13, 31, v12
	v_lshl_or_b32 v0, v4, 4, v0
	v_lshl_add_u64 v[112:113], s[4:5], 0, v[0:1]
	v_lshlrev_b64 v[0:1], 11, v[12:13]
	v_bitop3_b32 v4, v12, 7, v91 bitop3:0x48
	v_lshlrev_b64 v[10:11], 10, v[8:9]
	v_lshlrev_b64 v[14:15], 10, v[12:13]
	v_lshl_or_b32 v0, v4, 4, v0
	v_lshlrev_b32_e32 v147, 7, v18
	v_lshlrev_b32_e32 v152, 2, v151
	v_lshl_add_u64 v[108:109], s[4:5], 0, v[16:17]
	v_lshl_add_u64 v[114:115], s[4:5], 0, v[0:1]
	v_lshlrev_b64 v[116:117], 1, v[2:3]
	v_lshlrev_b64 v[118:119], 1, v[6:7]
	v_lshlrev_b64 v[120:121], 1, v[10:11]
	v_lshlrev_b64 v[122:123], 1, v[14:15]
	s_mov_b32 s2, s74
	v_writelane_b32 v255, 0, 1
	v_writelane_b32 v255, 0, 2
	s_cmpk_eq_i32 s23, 0x200
	s_cbranch_scc0 .LBB0_730
	s_cmpk_eq_i32 s1, 0x210
	s_cbranch_scc0 .LBB0_730
	v_writelane_b32 v255, 1, 2

; DEVI char* wsp(const Params& P, size_t off) { asm volatile("" : "+s"(off)); return P.ws + off; }
; #define ZERO_ACC(a) _Pragma("unroll") for (int m_ = 0; m_ < 4; ++m_) _Pragma("unroll") for (int n_ = 0; n_ < 4; ++n_) a[m_][n_] = f32x4{0.f, 0.f, 0.f, 0.f}
; template <int GATE>
; DEVI void gemm_core_t(f32x4 (&acc)[4][4], const bfu* __restrict__ A, int lda,
;                     const bfu* __restrict__ B, int ldb, int K, char* smem, int tid, const bfu* __restrict__ B2 = nullptr) {
;     ...
;   __syncthreads();
;   stage_tile(A, lda, 0, smem, tid);
;   if (GATE) stage_tile_gate(B, B2, 0, smem + 16384, tid); else stage_tile(B, ldb, 0, smem + 16384, tid);
; template <int BR, int IN, int OUT>
; DEVI void p6_branch(const Params& P, int pm, int pn, float* macc, char* smem, int tid) {
;   asm volatile("" : "+s"(pm), "+s"(pn));
;   const bfu* Z = (const bfu*)wsp(P, O_Z);
;   bfu* M = (bfu*)wsp(P, O_CB);
;   const bfu* A = (const bfu*)wsp(P, BR == 0 ? O_UA : BR == 1 ? O_UB : O_UC) + (long)pm * 128 * 1024;
;   const bfu* B = (const bfu*)wsp(P, BR == 0 ? O_WOA : BR == 1 ? O_WOB : O_WOC) + (long)pn * 128 * 1024;
;   f32x4 acc[4][4]; ZERO_ACC(acc);
;   gemm_core(acc, A, 1024, B, 1024, 1024, smem, tid);
.LBB0_734:
	s_mov_b64 s[42:43], 0x18d82000
	v_readlane_b32 vcc_lo, v255, 1
	v_readlane_b32 vcc_hi, v255, 2
	s_nop 0
	s_cmp_eq_u32 vcc_lo, 2
	s_cbranch_scc1 .Lp6_mode_ok
	s_cmp_eq_u32 vcc_hi, 1
	s_cbranch_scc0 .Lp6_mode_ok
	s_cmpk_gt_i32 s2, 0x1ff
	s_cbranch_scc0 .Lp6_mode_ok
	v_writelane_b32 v255, 1, 1
.Lp6_mode_ok:
	s_mov_b32 s46, s40
	s_mov_b32 s48, s26
	s_ashr_i32 s47, s46, 31
	s_ashr_i32 s49, s48, 31
	s_mov_b64 s[44:45], 0x8582000
	s_mov_b64 s[50:51], 0x17d02000
	s_mov_b64 s[52:53], 0x16c82000
	s_lshl_b64 s[54:55], s[46:47], 18
	s_lshl_b64 s[58:59], s[48:49], 18
	s_add_u32 s24, s30, s52
	s_addc_u32 s27, s31, s53
	s_add_u32 s60, s24, s54
	s_mov_b64 s[56:57], 0x1c00000
	s_addc_u32 s61, s27, s55
	s_add_u32 s24, s30, s56
	s_addc_u32 s27, s31, s57
	s_add_u32 s62, s24, s58
	v_lshl_add_u64 v[0:1], s[60:61], 0, v[116:117]
	v_lshlrev_b32_e32 v88, 1, v100
	v_readfirstlane_b32 s24, v101
	v_lshl_add_u64 v[0:1], v[0:1], 0, v[88:89]
	s_mov_b32 m0, s24
	s_barrier
	global_load_lds_dwordx4 v[0:1], off
	v_lshl_add_u64 v[0:1], s[60:61], 0, v[118:119]
	v_lshlrev_b32_e32 v124, 1, v102
	v_mov_b32_e32 v125, v89
	v_readfirstlane_b32 s24, v103
	v_lshl_add_u64 v[0:1], v[0:1], 0, v[124:125]
	s_mov_b32 m0, s24
	v_lshlrev_b32_e32 v126, 1, v104
	global_load_lds_dwordx4 v[0:1], off
	v_lshl_add_u64 v[0:1], s[60:61], 0, v[120:121]
	v_mov_b32_e32 v127, v89
	v_readfirstlane_b32 s24, v105
	v_lshl_add_u64 v[0:1], v[0:1], 0, v[126:127]
	s_mov_b32 m0, s24
	v_lshlrev_b32_e32 v128, 1, v106
	global_load_lds_dwordx4 v[0:1], off
	v_lshl_add_u64 v[0:1], s[60:61], 0, v[122:123]
	v_mov_b32_e32 v129, v89
	v_readfirstlane_b32 s24, v107
	s_addc_u32 s63, s27, s59
	v_lshl_add_u64 v[0:1], v[0:1], 0, v[128:129]
	s_mov_b32 m0, s24
	v_add_u32_e32 v153, 0x4000, v101
	global_load_lds_dwordx4 v[0:1], off
	v_lshl_add_u64 v[0:1], s[62:63], 0, v[116:117]
	v_readfirstlane_b32 s24, v153
	v_lshl_add_u64 v[0:1], v[0:1], 0, v[88:89]
	s_mov_b32 m0, s24
	v_add_u32_e32 v154, 0x5000, v101
	global_load_lds_dwordx4 v[0:1], off
	v_lshl_add_u64 v[0:1], s[62:63], 0, v[118:119]
	v_readfirstlane_b32 s24, v154
	v_lshl_add_u64 v[0:1], v[0:1], 0, v[124:125]
	s_mov_b32 m0, s24
	v_add_u32_e32 v155, 0x6000, v101
	global_load_lds_dwordx4 v[0:1], off
	v_lshl_add_u64 v[0:1], s[62:63], 0, v[120:121]
	v_readfirstlane_b32 s24, v155
	v_lshl_add_u64 v[0:1], v[0:1], 0, v[126:127]
	s_mov_b32 m0, s24
	v_add_u32_e32 v156, 0x7000, v101
	global_load_lds_dwordx4 v[0:1], off
	v_lshl_add_u64 v[0:1], s[62:63], 0, v[122:123]
	v_readfirstlane_b32 s24, v156
	v_lshl_add_u64 v[0:1], v[0:1], 0, v[128:129]
	s_mov_b32 m0, s24
	s_add_u32 s52, s52, s54
	global_load_lds_dwordx4 v[0:1], off
	s_addc_u32 s53, s53, s55
	v_lshl_add_u64 v[130:131], v[108:109], 0, s[52:53]
	v_lshl_add_u64 v[132:133], v[110:111], 0, s[52:53]
	v_lshl_add_u64 v[134:135], v[112:113], 0, s[52:53]
	v_lshl_add_u64 v[136:137], v[114:115], 0, s[52:53]
	s_add_u32 s52, s56, s58
	s_addc_u32 s53, s57, s59
	v_mov_b32_e32 v0, 0
	v_lshl_add_u64 v[138:139], v[108:109], 0, s[52:53]
	v_lshl_add_u64 v[140:141], v[110:111], 0, s[52:53]
	v_lshl_add_u64 v[142:143], v[112:113], 0, s[52:53]
	v_lshl_add_u64 v[144:145], v[114:115], 0, s[52:53]
	s_mov_b64 s[52:53], 0
	s_mov_b32 s24, 0x8000
	v_readlane_b32 vcc_lo, v255, 1
	s_nop 0
	s_cmp_eq_u32 vcc_lo, 2
	s_cbranch_scc0 .Lp6_fullk
	s_movk_i32 s52, 0x700
.Lp6_fullk:
	v_mov_b32_e32 v1, v0
	v_mov_b32_e32 v2, v0
	v_mov_b32_e32 v3, v0
	v_mov_b32_e32 v4, v0
	v_mov_b32_e32 v5, v0
	v_mov_b32_e32 v6, v0
	v_mov_b32_e32 v7, v0
	v_mov_b32_e32 v8, v0
	v_mov_b32_e32 v9, v0
	v_mov_b32_e32 v10, v0
	v_mov_b32_e32 v11, v0
	v_mov_b32_e32 v12, v0
	v_mov_b32_e32 v13, v0
	v_mov_b32_e32 v14, v0
	v_mov_b32_e32 v15, v0
	v_mov_b32_e32 v16, v0
	v_mov_b32_e32 v17, v0
	v_mov_b32_e32 v18, v0
	v_mov_b32_e32 v19, v0
	v_mov_b32_e32 v20, v0
	v_mov_b32_e32 v21, v0
	v_mov_b32_e32 v22, v0
	v_mov_b32_e32 v23, v0
	v_mov_b32_e32 v24, v0
	v_mov_b32_e32 v25, v0
	v_mov_b32_e32 v26, v0
	v_mov_b32_e32 v27, v0
	v_mov_b32_e32 v28, v0
	v_mov_b32_e32 v29, v0
	v_mov_b32_e32 v30, v0
	v_mov_b32_e32 v31, v0
	v_mov_b32_e32 v32, v0
	v_mov_b32_e32 v33, v0
	v_mov_b32_e32 v34, v0
	v_mov_b32_e32 v35, v0
	v_mov_b32_e32 v36, v0
	v_mov_b32_e32 v37, v0
	v_mov_b32_e32 v38, v0
	v_mov_b32_e32 v39, v0
	v_mov_b32_e32 v40, v0
	v_mov_b32_e32 v41, v0
	v_mov_b32_e32 v42, v0
	v_mov_b32_e32 v43, v0
	v_mov_b32_e32 v44, v0
	v_mov_b32_e32 v45, v0
	v_mov_b32_e32 v46, v0
	v_mov_b32_e32 v47, v0
	v_mov_b32_e32 v48, v0
	v_mov_b32_e32 v49, v0
	v_mov_b32_e32 v50, v0
	v_mov_b32_e32 v51, v0
	v_mov_b32_e32 v52, v0
	v_mov_b32_e32 v53, v0
	v_mov_b32_e32 v54, v0
	v_mov_b32_e32 v55, v0
	v_mov_b32_e32 v56, v0
	v_mov_b32_e32 v57, v0
	v_mov_b32_e32 v58, v0
	v_mov_b32_e32 v59, v0
	v_mov_b32_e32 v60, v0
	v_mov_b32_e32 v61, v0
	v_mov_b32_e32 v62, v0
	v_mov_b32_e32 v63, v0
; template <int GATE>
; DEVI void gemm_core_t(f32x4 (&acc)[4][4], const bfu* __restrict__ A, int lda,
;                     const bfu* __restrict__ B, int ldb, int K, char* smem, int tid, const bfu* __restrict__ B2 = nullptr) {
;     ...
;   for (int t = 0; t < nt; ++t) {
;     asm volatile("s_waitcnt vmcnt(0)" ::: "memory");
;     __syncthreads();
;     char* cur = smem + (t & 1) * 32768;
;     if (t + 1 < nt) {
;       char* nx = smem + ((t + 1) & 1) * 32768;
;       stage_tile(A, lda, (t + 1) * 64, nx, tid);
;       if (GATE) stage_tile_gate(B, B2, (t + 1) * 64, nx + 16384, tid); else stage_tile(B, ldb, (t + 1) * 64, nx + 16384, tid);
;     }
; #pragma unroll
;     for (int kk = 0; kk < 2; ++kk) {
;       bf16x8 af[4], bfr[4];
; #pragma unroll
;       for (int m = 0; m < 4; ++m) af[m] = ldfrag(cur, wr * 64 + m * 16 + fr, kk * 4 + fq);
; #pragma unroll
;       for (int n = 0; n < 4; ++n) bfr[n] = ldfrag(cur + 16384, wc * 64 + n * 16 + fr, kk * 4 + fq);
; #pragma unroll
;       for (int m = 0; m < 4; ++m)
; #pragma unroll
;         for (int n = 0; n < 4; ++n)
;           acc[m][n] = __builtin_amdgcn_mfma_f32_16x16x32_bf16(af[m], bfr[n], acc[m][n], 0, 0, 0);
;     }
;   }
.LBB0_735:
	s_add_i32 s27, s24, 0xffff8000
	s_and_b32 s41, s27, 0x8000
	s_and_b32 s27, s24, 0x8000
	v_add_u32_e32 v125, s27, v101
	v_add_u32_e32 v127, 0x1000, v125
	v_readfirstlane_b32 s49, v125
	v_lshl_add_u64 v[158:159], v[130:131], 0, s[52:53]
	s_mov_b32 m0, s49
	v_readfirstlane_b32 s49, v127
	v_add_u32_e32 v127, 0x2000, v125
	s_waitcnt vmcnt(0)
	s_waitcnt vmcnt(0) lgkmcnt(0)
	s_barrier
	global_load_lds_dwordx4 v[158:159], off
	v_lshl_add_u64 v[158:159], v[132:133], 0, s[52:53]
	s_mov_b32 m0, s49
	v_readfirstlane_b32 s49, v127
	v_add_u32_e32 v127, 0x3000, v125
	global_load_lds_dwordx4 v[158:159], off
	v_lshl_add_u64 v[158:159], v[134:135], 0, s[52:53]
	s_mov_b32 m0, s49
	v_readfirstlane_b32 s49, v127
	v_add_u32_e32 v127, 0x4000, v125
	global_load_lds_dwordx4 v[158:159], off
	v_lshl_add_u64 v[158:159], v[136:137], 0, s[52:53]
	s_mov_b32 m0, s49
	v_readfirstlane_b32 s49, v127
	v_add_u32_e32 v127, 0x5000, v125
	global_load_lds_dwordx4 v[158:159], off
	v_lshl_add_u64 v[158:159], v[138:139], 0, s[52:53]
	s_mov_b32 m0, s49
	v_readfirstlane_b32 s49, v127
	v_add_u32_e32 v127, 0x6000, v125
	global_load_lds_dwordx4 v[158:159], off
	v_lshl_add_u64 v[158:159], v[140:141], 0, s[52:53]
	s_mov_b32 m0, s49
	v_readfirstlane_b32 s49, v127
	v_add_u32_e32 v125, 0x7000, v125
	global_load_lds_dwordx4 v[158:159], off
	v_lshl_add_u64 v[158:159], v[142:143], 0, s[52:53]
	s_mov_b32 m0, s49
	v_readfirstlane_b32 s49, v125
	global_load_lds_dwordx4 v[158:159], off
	v_lshl_add_u64 v[158:159], v[144:145], 0, s[52:53]
	s_mov_b32 m0, s49
	v_or_b32_e32 v125, s41, v146
	global_load_lds_dwordx4 v[158:159], off
	v_add_u32_e32 v127, v125, v147
	v_add_u32_e32 v125, v125, v148
	ds_read_b128 v[158:161], v127
	ds_read_b128 v[162:165], v127 offset:2048
	ds_read_b128 v[166:169], v127 offset:4096
	ds_read_b128 v[170:173], v127 offset:6144
	ds_read_b128 v[174:177], v125 offset:16384
	ds_read_b128 v[178:181], v125 offset:18432
	ds_read_b128 v[196:199], v125 offset:20480
	ds_read_b128 v[200:203], v125 offset:22528
	v_or_b32_e32 v125, s41, v149
	v_add_u32_e32 v127, v125, v147
	v_add_u32_e32 v125, v125, v148
	s_waitcnt lgkmcnt(0)
	v_mfma_f32_16x16x32_bf16 v[60:63], v[158:161], v[174:177], v[60:63]
	s_add_u32 s52, s52, 0x80
	s_addc_u32 s53, s53, 0
	s_add_i32 s24, s24, 0x8000
	v_mfma_f32_16x16x32_bf16 v[56:59], v[158:161], v[178:181], v[56:59]
	s_cmpk_lg_i32 s52, 0x780
	v_mfma_f32_16x16x32_bf16 v[52:55], v[158:161], v[196:199], v[52:55]
	v_mfma_f32_16x16x32_bf16 v[48:51], v[158:161], v[200:203], v[48:51]
	v_mfma_f32_16x16x32_bf16 v[44:47], v[162:165], v[174:177], v[44:47]
	v_mfma_f32_16x16x32_bf16 v[40:43], v[162:165], v[178:181], v[40:43]
	v_mfma_f32_16x16x32_bf16 v[36:39], v[162:165], v[196:199], v[36:39]
	v_mfma_f32_16x16x32_bf16 v[32:35], v[162:165], v[200:203], v[32:35]
	v_mfma_f32_16x16x32_bf16 v[28:31], v[166:169], v[174:177], v[28:31]
	v_mfma_f32_16x16x32_bf16 v[24:27], v[166:169], v[178:181], v[24:27]
	v_mfma_f32_16x16x32_bf16 v[20:23], v[166:169], v[196:199], v[20:23]
	v_mfma_f32_16x16x32_bf16 v[16:19], v[166:169], v[200:203], v[16:19]
	v_mfma_f32_16x16x32_bf16 v[12:15], v[170:173], v[174:177], v[12:15]
	v_mfma_f32_16x16x32_bf16 v[8:11], v[170:173], v[178:181], v[8:11]
	v_mfma_f32_16x16x32_bf16 v[4:7], v[170:173], v[196:199], v[4:7]
	v_mfma_f32_16x16x32_bf16 v[0:3], v[170:173], v[200:203], v[0:3]
	ds_read_b128 v[158:161], v127
	ds_read_b128 v[162:165], v127 offset:2048
	ds_read_b128 v[166:169], v127 offset:4096
	ds_read_b128 v[170:173], v127 offset:6144
	ds_read_b128 v[174:177], v125 offset:16384
	ds_read_b128 v[178:181], v125 offset:18432
	ds_read_b128 v[196:199], v125 offset:20480
	ds_read_b128 v[200:203], v125 offset:22528
	s_waitcnt lgkmcnt(0)
	v_mfma_f32_16x16x32_bf16 v[60:63], v[158:161], v[174:177], v[60:63]
	v_mfma_f32_16x16x32_bf16 v[56:59], v[158:161], v[178:181], v[56:59]
	v_mfma_f32_16x16x32_bf16 v[52:55], v[158:161], v[196:199], v[52:55]
	v_mfma_f32_16x16x32_bf16 v[48:51], v[158:161], v[200:203], v[48:51]
	v_mfma_f32_16x16x32_bf16 v[44:47], v[162:165], v[174:177], v[44:47]
	v_mfma_f32_16x16x32_bf16 v[40:43], v[162:165], v[178:181], v[40:43]
	v_mfma_f32_16x16x32_bf16 v[36:39], v[162:165], v[196:199], v[36:39]
	v_mfma_f32_16x16x32_bf16 v[32:35], v[162:165], v[200:203], v[32:35]
	v_mfma_f32_16x16x32_bf16 v[28:31], v[166:169], v[174:177], v[28:31]
	v_mfma_f32_16x16x32_bf16 v[24:27], v[166:169], v[178:181], v[24:27]
	v_mfma_f32_16x16x32_bf16 v[20:23], v[166:169], v[196:199], v[20:23]
	v_mfma_f32_16x16x32_bf16 v[16:19], v[166:169], v[200:203], v[16:19]
	v_mfma_f32_16x16x32_bf16 v[12:15], v[170:173], v[174:177], v[12:15]
	v_mfma_f32_16x16x32_bf16 v[8:11], v[170:173], v[178:181], v[8:11]
	v_mfma_f32_16x16x32_bf16 v[4:7], v[170:173], v[196:199], v[4:7]
	v_mfma_f32_16x16x32_bf16 v[0:3], v[170:173], v[200:203], v[0:3]
	s_cbranch_scc1 .LBB0_735
	v_add_u32_e32 v125, s27, v146
	v_add_u32_e32 v127, v125, v147
	s_waitcnt vmcnt(0)
	s_waitcnt vmcnt(0)
	s_barrier
; template <int GATE>
; DEVI void gemm_core_t(f32x4 (&acc)[4][4], const bfu* __restrict__ A, int lda,
;                     const bfu* __restrict__ B, int ldb, int K, char* smem, int tid, const bfu* __restrict__ B2 = nullptr) {
;     ...
; #pragma unroll
;     for (int kk = 0; kk < 2; ++kk) {
;       bf16x8 af[4], bfr[4];
; #pragma unroll
;       for (int m = 0; m < 4; ++m) af[m] = ldfrag(cur, wr * 64 + m * 16 + fr, kk * 4 + fq);
; #pragma unroll
;       for (int n = 0; n < 4; ++n) bfr[n] = ldfrag(cur + 16384, wc * 64 + n * 16 + fr, kk * 4 + fq);
; #pragma unroll
;       for (int m = 0; m < 4; ++m)
; #pragma unroll
;         for (int n = 0; n < 4; ++n)
;           acc[m][n] = __builtin_amdgcn_mfma_f32_16x16x32_bf16(af[m], bfr[n], acc[m][n], 0, 0, 0);
;     }
; DEVI void epi_stage_f32(const f32x4 (&acc)[4][4], char* smem, int tid) {
;   const int wid = tid >> 6, lane = tid & 63, wr = wid >> 1, wc = wid & 1, fr = lane & 15, fq = lane >> 4;
;   float* T = reinterpret_cast<float*>(smem);
;   __syncthreads();
; #pragma unroll
;   for (int m = 0; m < 4; ++m)
; #pragma unroll
;     for (int n = 0; n < 4; ++n)
; #pragma unroll
;       for (int j = 0; j < 4; ++j)
;         T[(wr * 64 + m * 16 + fq * 4 + j) * 128 + wc * 64 + n * 16 + fr] = acc[m][n][j];
;   __syncthreads();
	ds_read_b128 v[130:133], v127
	v_add_u32_e32 v125, v125, v148
	ds_read_b128 v[134:137], v125 offset:16384
	ds_read_b128 v[138:141], v127 offset:2048
	ds_read_b128 v[142:145], v125 offset:18432
	ds_read_b128 v[158:161], v125 offset:20480
	ds_read_b128 v[162:165], v125 offset:22528
	s_waitcnt lgkmcnt(3)
	v_mfma_f32_16x16x32_bf16 v[44:47], v[138:141], v[134:137], v[44:47]
	v_add_u32_e32 v125, s27, v149
	s_add_u32 s42, s30, s42
	s_addc_u32 s43, s31, s43
	v_mfma_f32_16x16x32_bf16 v[60:63], v[130:133], v[134:137], v[60:63]
	s_add_u32 s44, s30, s44
	s_addc_u32 s45, s31, s45
	v_add_u32_e32 v157, 0x6400, v150
	s_waitcnt lgkmcnt(2)
	v_mfma_f32_16x16x32_bf16 v[56:59], v[130:133], v[142:145], v[56:59]
	s_add_u32 s50, s30, s50
	s_addc_u32 s51, s31, s51
	s_lshl_b64 s[46:47], s[46:47], 7
	s_waitcnt lgkmcnt(1)
	v_mfma_f32_16x16x32_bf16 v[52:55], v[130:133], v[158:161], v[52:55]
	s_mov_b32 s24, 0
	s_waitcnt lgkmcnt(0)
	v_mfma_f32_16x16x32_bf16 v[48:51], v[130:133], v[162:165], v[48:51]
	v_mfma_f32_16x16x32_bf16 v[40:43], v[138:141], v[142:145], v[40:43]
	v_mfma_f32_16x16x32_bf16 v[36:39], v[138:141], v[158:161], v[36:39]
	v_mfma_f32_16x16x32_bf16 v[32:35], v[138:141], v[162:165], v[32:35]
	ds_read_b128 v[130:133], v127 offset:4096
	ds_read_b128 v[138:141], v127 offset:6144
	v_add_u32_e32 v127, v125, v147
	v_add_u32_e32 v125, v125, v148
	s_waitcnt lgkmcnt(1)
	v_mfma_f32_16x16x32_bf16 v[28:31], v[130:133], v[134:137], v[28:31]
	v_mfma_f32_16x16x32_bf16 v[24:27], v[130:133], v[142:145], v[24:27]
	v_mfma_f32_16x16x32_bf16 v[20:23], v[130:133], v[158:161], v[20:23]
	v_mfma_f32_16x16x32_bf16 v[16:19], v[130:133], v[162:165], v[16:19]
	ds_read_b128 v[130:133], v127
	s_waitcnt lgkmcnt(1)
	v_mfma_f32_16x16x32_bf16 v[12:15], v[138:141], v[134:137], v[12:15]
	ds_read_b128 v[134:137], v125 offset:16384
	v_mfma_f32_16x16x32_bf16 v[8:11], v[138:141], v[142:145], v[8:11]
	v_mfma_f32_16x16x32_bf16 v[4:7], v[138:141], v[158:161], v[4:7]
	ds_read_b128 v[142:145], v127 offset:2048
	ds_read_b128 v[158:161], v125 offset:18432
	ds_read_b128 v[166:169], v125 offset:22528
	v_mfma_f32_16x16x32_bf16 v[0:3], v[138:141], v[162:165], v[0:3]
	ds_read_b128 v[162:165], v125 offset:20480
	ds_read_b128 v[170:173], v127 offset:4096
	ds_read_b128 v[174:177], v127 offset:6144
	v_add_u32_e32 v140, 0x400, v150
	s_waitcnt lgkmcnt(6)
	v_mfma_f32_16x16x32_bf16 v[60:63], v[130:133], v[134:137], v[60:63]
	v_add_u32_e32 v141, 0x2000, v150
	s_waitcnt lgkmcnt(0)
	s_barrier
	v_mfma_f32_16x16x32_bf16 v[56:59], v[130:133], v[158:161], v[56:59]
	s_nop 7
	ds_write2_b32 v150, v60, v56 offset1:16
	ds_write2_b32 v150, v61, v57 offset0:128 offset1:144
	v_mfma_f32_16x16x32_bf16 v[52:55], v[130:133], v[162:165], v[52:55]
	ds_write2_b32 v140, v62, v58 offset1:16
	ds_write2_b32 v140, v63, v59 offset0:128 offset1:144
	v_mfma_f32_16x16x32_bf16 v[48:51], v[130:133], v[166:169], v[48:51]
	s_nop 7
	ds_write2_b32 v150, v52, v48 offset0:32 offset1:48
	ds_write2_b32 v150, v53, v49 offset0:160 offset1:176
	ds_write2_b32 v140, v54, v50 offset0:32 offset1:48
	v_mfma_f32_16x16x32_bf16 v[44:47], v[142:145], v[134:137], v[44:47]
	ds_write2_b32 v140, v55, v51 offset0:160 offset1:176
	v_mfma_f32_16x16x32_bf16 v[40:43], v[142:145], v[158:161], v[40:43]
	v_mfma_f32_16x16x32_bf16 v[36:39], v[142:145], v[162:165], v[36:39]
	v_mfma_f32_16x16x32_bf16 v[32:35], v[142:145], v[166:169], v[32:35]
	v_add_u32_e32 v142, 0x2400, v150
	v_add_u32_e32 v143, 0x4000, v150
	v_add_u32_e32 v144, 0x4400, v150
	v_mfma_f32_16x16x32_bf16 v[28:31], v[170:173], v[134:137], v[28:31]
	v_add_u32_e32 v145, 0x6000, v150
	s_nop 0
	ds_write2_b32 v141, v44, v40 offset1:16
	ds_write2_b32 v141, v45, v41 offset0:128 offset1:144
	v_mfma_f32_16x16x32_bf16 v[24:27], v[170:173], v[158:161], v[24:27]
	ds_write2_b32 v142, v46, v42 offset1:16
	ds_write2_b32 v142, v47, v43 offset0:128 offset1:144
	ds_write2_b32 v141, v36, v32 offset0:32 offset1:48
	ds_write2_b32 v141, v37, v33 offset0:160 offset1:176
	ds_write2_b32 v142, v38, v34 offset0:32 offset1:48
	ds_write2_b32 v142, v39, v35 offset0:160 offset1:176
	v_mfma_f32_16x16x32_bf16 v[20:23], v[170:173], v[162:165], v[20:23]
	s_nop 0
	ds_write2_b32 v143, v28, v24 offset1:16
	ds_write2_b32 v143, v29, v25 offset0:128 offset1:144
	v_mfma_f32_16x16x32_bf16 v[16:19], v[170:173], v[166:169], v[16:19]
	ds_write2_b32 v144, v30, v26 offset1:16
	ds_write2_b32 v144, v31, v27 offset0:128 offset1:144
	s_nop 5
	ds_write2_b32 v143, v20, v16 offset0:32 offset1:48
	ds_write2_b32 v143, v21, v17 offset0:160 offset1:176
	ds_write2_b32 v144, v22, v18 offset0:32 offset1:48
	ds_write2_b32 v144, v23, v19 offset0:160 offset1:176
	v_mfma_f32_16x16x32_bf16 v[12:15], v[174:177], v[134:137], v[12:15]
	v_mfma_f32_16x16x32_bf16 v[8:11], v[174:177], v[158:161], v[8:11]
	s_nop 7
	ds_write2_b32 v145, v12, v8 offset1:16
	ds_write2_b32 v145, v13, v9 offset0:128 offset1:144
	v_mfma_f32_16x16x32_bf16 v[4:7], v[174:177], v[162:165], v[4:7]
	ds_write2_b32 v157, v14, v10 offset1:16
	ds_write2_b32 v157, v15, v11 offset0:128 offset1:144
	v_mfma_f32_16x16x32_bf16 v[0:3], v[174:177], v[166:169], v[0:3]
	s_nop 7
	ds_write2_b32 v145, v4, v0 offset0:32 offset1:48
	ds_write2_b32 v145, v5, v1 offset0:160 offset1:176
	ds_write2_b32 v157, v6, v2 offset0:32 offset1:48
	ds_write2_b32 v157, v7, v3 offset0:160 offset1:176
	v_lshl_or_b32 v4, s48, 7, v151
	v_ashrrev_i32_e32 v5, 31, v4
	v_lshl_add_u64 v[0:1], v[4:5], 1, s[50:51]
	v_lshl_add_u64 v[2:3], v[4:5], 2, s[42:43]
	v_lshlrev_b64 v[4:5], 1, v[4:5]
	s_waitcnt lgkmcnt(0)
	s_barrier
	v_readlane_b32 vcc_lo, v255, 1
	s_nop 0
	s_cmp_eq_u32 vcc_lo, 2
	s_cbranch_scc0 .LBB0_737
	s_mov_b64 exec, 0
; DEVI float sigmoidf_(float x) { return 1.f / (1.f + __expf(-x)); }
; template <int BR, int IN, int OUT>
; DEVI void p6_branch(const Params& P, int pm, int pn, float* macc, char* smem, int tid) {
;     ...
; #pragma unroll 8
;   for (int q = 0; q < 16; ++q) {
;     const int id = tid + 256 * q, row = id >> 5, c4 = id & 31;
;     const long grow = (long)pm * 128 + row;
;     const int gcol = pn * 128 + c4 * 4;
;     float4 a = *reinterpret_cast<const float4*>(T + row * 128 + c4 * 4);
;     float g[4];
;     load4bf(Z + grow * NCOL + (9 + BR) * 1024 + gcol, g);
;     float v[4] = {sigmoidf_(g[0]) * a.x, sigmoidf_(g[1]) * a.y, sigmoidf_(g[2]) * a.z, sigmoidf_(g[3]) * a.w};
;     if (IN == 1) {
;       float mo[4]; load4bf(M + grow * 1024 + gcol, mo);
;       v[0] += mo[0]; v[1] += mo[1]; v[2] += mo[2]; v[3] += mo[3];
.LBB0_737:
	v_add_u32_e32 v242, s24, v91
	v_ashrrev_i32_e32 v240, 5, v242
	v_ashrrev_i32_e32 v241, 31, v240
	v_lshl_add_u64 v[244:245], s[46:47], 0, v[240:241]
	v_mov_b64_e32 v[240:241], s[44:45]
	v_mad_u64_u32 v[246:247], s[48:49], v244, s22, v[240:241]
	v_mad_i32_i24 v247, v245, s22, v247
	v_lshl_add_u64 v[246:247], v[246:247], 0, v[4:5]
	v_add_co_u32_e32 v246, vcc, 0x5000, v246
	s_nop 1
	v_addc_co_u32_e32 v247, vcc, 0, v247, vcc
	global_load_dwordx2 v[208:209], v[246:247], off offset:2048
	v_add_u32_e32 v242, s24, v91
	v_ashrrev_i32_e32 v240, 5, v242
	v_ashrrev_i32_e32 v241, 31, v240
	v_lshl_add_u64 v[244:245], s[46:47], 0, v[240:241]
	v_lshlrev_b64 v[246:247], 11, v[244:245]
	v_lshl_add_u64 v[246:247], v[0:1], 0, v[246:247]
	global_load_dwordx2 v[210:211], v[246:247], off
	v_add_u32_e32 v242, s24, v91
	v_mov_b64_e32 v[240:241], s[44:45]
	v_add_u32_e32 v243, 0x100, v242
	v_ashrrev_i32_e32 v244, 5, v243
	v_ashrrev_i32_e32 v245, 31, v244
	v_lshl_add_u64 v[246:247], s[46:47], 0, v[244:245]
	v_mad_u64_u32 v[244:245], s[48:49], v246, s22, v[240:241]
	v_mad_i32_i24 v245, v247, s22, v245
	v_lshl_add_u64 v[244:245], v[244:245], 0, v[4:5]
	v_add_co_u32_e32 v244, vcc, s21, v244
	s_nop 1
	v_addc_co_u32_e32 v245, vcc, 0, v245, vcc
	global_load_dwordx2 v[212:213], v[244:245], off offset:2048
	v_add_u32_e32 v240, s24, v91
	v_add_u32_e32 v241, 0x100, v240
	v_ashrrev_i32_e32 v242, 5, v241
	v_ashrrev_i32_e32 v243, 31, v242
	v_lshl_add_u64 v[244:245], s[46:47], 0, v[242:243]
	v_lshlrev_b64 v[242:243], 11, v[244:245]
	v_lshl_add_u64 v[242:243], v[0:1], 0, v[242:243]
	global_load_dwordx2 v[214:215], v[242:243], off
	v_add_u32_e32 v242, s24, v91
	v_mov_b64_e32 v[240:241], s[44:45]
	v_add_u32_e32 v243, 0x200, v242
	v_ashrrev_i32_e32 v244, 5, v243
	v_ashrrev_i32_e32 v245, 31, v244
	v_lshl_add_u64 v[246:247], s[46:47], 0, v[244:245]
	v_mad_u64_u32 v[244:245], s[48:49], v246, s22, v[240:241]
	v_mad_i32_i24 v245, v247, s22, v245
	v_lshl_add_u64 v[244:245], v[244:245], 0, v[4:5]
	v_add_co_u32_e32 v244, vcc, s21, v244
	s_nop 1
	v_addc_co_u32_e32 v245, vcc, 0, v245, vcc
	global_load_dwordx2 v[216:217], v[244:245], off offset:2048
	v_add_u32_e32 v240, s24, v91
	v_add_u32_e32 v241, 0x200, v240
	v_ashrrev_i32_e32 v242, 5, v241
	v_ashrrev_i32_e32 v243, 31, v242
	v_lshl_add_u64 v[244:245], s[46:47], 0, v[242:243]
	v_lshlrev_b64 v[242:243], 11, v[244:245]
	v_lshl_add_u64 v[242:243], v[0:1], 0, v[242:243]
	global_load_dwordx2 v[218:219], v[242:243], off
	v_add_u32_e32 v242, s24, v91
	v_mov_b64_e32 v[240:241], s[44:45]
	v_add_u32_e32 v243, 0x300, v242
	v_ashrrev_i32_e32 v244, 5, v243
	v_ashrrev_i32_e32 v245, 31, v244
	v_lshl_add_u64 v[246:247], s[46:47], 0, v[244:245]
	v_mad_u64_u32 v[244:245], s[48:49], v246, s22, v[240:241]
	v_mad_i32_i24 v245, v247, s22, v245
	v_lshl_add_u64 v[244:245], v[244:245], 0, v[4:5]
	v_add_co_u32_e32 v244, vcc, s21, v244
	s_nop 1
	v_addc_co_u32_e32 v245, vcc, 0, v245, vcc
	global_load_dwordx2 v[220:221], v[244:245], off offset:2048
	v_add_u32_e32 v240, s24, v91
	v_add_u32_e32 v241, 0x300, v240
	v_ashrrev_i32_e32 v242, 5, v241
	v_ashrrev_i32_e32 v243, 31, v242
	v_lshl_add_u64 v[244:245], s[46:47], 0, v[242:243]
	v_lshlrev_b64 v[242:243], 11, v[244:245]
	v_lshl_add_u64 v[242:243], v[0:1], 0, v[242:243]
	global_load_dwordx2 v[222:223], v[242:243], off
	v_add_u32_e32 v242, s24, v91
	v_mov_b64_e32 v[240:241], s[44:45]
	v_add_u32_e32 v243, 0x400, v242
	v_ashrrev_i32_e32 v244, 5, v243
	v_ashrrev_i32_e32 v245, 31, v244
	v_lshl_add_u64 v[246:247], s[46:47], 0, v[244:245]
	v_mad_u64_u32 v[244:245], s[48:49], v246, s22, v[240:241]
	v_mad_i32_i24 v245, v247, s22, v245
	v_lshl_add_u64 v[244:245], v[244:245], 0, v[4:5]
	v_add_co_u32_e32 v244, vcc, s21, v244
	s_nop 1
	v_addc_co_u32_e32 v245, vcc, 0, v245, vcc
	global_load_dwordx2 v[224:225], v[244:245], off offset:2048
	v_add_u32_e32 v240, s24, v91
	v_add_u32_e32 v241, 0x400, v240
	v_ashrrev_i32_e32 v242, 5, v241
	v_ashrrev_i32_e32 v243, 31, v242
	v_lshl_add_u64 v[244:245], s[46:47], 0, v[242:243]
	v_lshlrev_b64 v[242:243], 11, v[244:245]
	v_lshl_add_u64 v[242:243], v[0:1], 0, v[242:243]
	global_load_dwordx2 v[226:227], v[242:243], off
	v_add_u32_e32 v242, s24, v91
	v_mov_b64_e32 v[240:241], s[44:45]
	v_add_u32_e32 v243, 0x500, v242
	v_ashrrev_i32_e32 v244, 5, v243
	v_ashrrev_i32_e32 v245, 31, v244
	v_lshl_add_u64 v[246:247], s[46:47], 0, v[244:245]
	v_mad_u64_u32 v[244:245], s[48:49], v246, s22, v[240:241]
	v_mad_i32_i24 v245, v247, s22, v245
	v_lshl_add_u64 v[244:245], v[244:245], 0, v[4:5]
	v_add_co_u32_e32 v244, vcc, s21, v244
	s_nop 1
	v_addc_co_u32_e32 v245, vcc, 0, v245, vcc
	global_load_dwordx2 v[228:229], v[244:245], off offset:2048
	v_add_u32_e32 v240, s24, v91
	v_add_u32_e32 v241, 0x500, v240
	v_ashrrev_i32_e32 v242, 5, v241
	v_ashrrev_i32_e32 v243, 31, v242
	v_lshl_add_u64 v[244:245], s[46:47], 0, v[242:243]
	v_lshlrev_b64 v[242:243], 11, v[244:245]
	v_lshl_add_u64 v[242:243], v[0:1], 0, v[242:243]
	global_load_dwordx2 v[230:231], v[242:243], off
	v_add_u32_e32 v242, s24, v91
	v_mov_b64_e32 v[240:241], s[44:45]
	v_add_u32_e32 v243, 0x600, v242
	v_ashrrev_i32_e32 v244, 5, v243
	v_ashrrev_i32_e32 v245, 31, v244
	v_lshl_add_u64 v[246:247], s[46:47], 0, v[244:245]
	v_mad_u64_u32 v[244:245], s[48:49], v246, s22, v[240:241]
	v_mad_i32_i24 v245, v247, s22, v245
	v_lshl_add_u64 v[244:245], v[244:245], 0, v[4:5]
	v_add_co_u32_e32 v244, vcc, s21, v244
	s_nop 1
	v_addc_co_u32_e32 v245, vcc, 0, v245, vcc
	global_load_dwordx2 v[232:233], v[244:245], off offset:2048
	v_add_u32_e32 v240, s24, v91
	v_add_u32_e32 v241, 0x600, v240
	v_ashrrev_i32_e32 v242, 5, v241
	v_ashrrev_i32_e32 v243, 31, v242
	v_lshl_add_u64 v[244:245], s[46:47], 0, v[242:243]
	v_lshlrev_b64 v[242:243], 11, v[244:245]
	v_lshl_add_u64 v[242:243], v[0:1], 0, v[242:243]
	global_load_dwordx2 v[234:235], v[242:243], off
	v_add_u32_e32 v242, s24, v91
	v_mov_b64_e32 v[240:241], s[44:45]
	v_add_u32_e32 v242, 0x700, v242
	v_ashrrev_i32_e32 v242, 5, v242
	v_ashrrev_i32_e32 v243, 31, v242
	v_lshl_add_u64 v[244:245], s[46:47], 0, v[242:243]
	v_mad_u64_u32 v[240:241], s[48:49], v244, s22, v[240:241]
	v_mad_i32_i24 v241, v245, s22, v241
	v_lshl_add_u64 v[240:241], v[240:241], 0, v[4:5]
	v_add_co_u32_e32 v240, vcc, s21, v240
	s_nop 1
	v_addc_co_u32_e32 v241, vcc, 0, v241, vcc
	global_load_dwordx2 v[236:237], v[240:241], off offset:2048
	v_add_u32_e32 v242, s24, v91
	v_add_u32_e32 v242, 0x700, v242
	v_ashrrev_i32_e32 v242, 5, v242
	v_ashrrev_i32_e32 v243, 31, v242
	v_lshl_add_u64 v[244:245], s[46:47], 0, v[242:243]
	v_lshlrev_b64 v[240:241], 11, v[244:245]
	v_lshl_add_u64 v[240:241], v[0:1], 0, v[240:241]
	global_load_dwordx2 v[238:239], v[240:241], off
	s_waitcnt vmcnt(0)
; DEVI float sigmoidf_(float x) { return 1.f / (1.f + __expf(-x)); }
; template <int BR, int IN, int OUT>
; DEVI void p6_branch(const Params& P, int pm, int pn, float* macc, char* smem, int tid) {
;     ...
;   for (int q = 0; q < 16; ++q) {
;     const int id = tid + 256 * q, row = id >> 5, c4 = id & 31;
;     const long grow = (long)pm * 128 + row;
;     const int gcol = pn * 128 + c4 * 4;
;     float4 a = *reinterpret_cast<const float4*>(T + row * 128 + c4 * 4);
;     float g[4];
;     load4bf(Z + grow * NCOL + (9 + BR) * 1024 + gcol, g);
;     float v[4] = {sigmoidf_(g[0]) * a.x, sigmoidf_(g[1]) * a.y, sigmoidf_(g[2]) * a.z, sigmoidf_(g[3]) * a.w};
;     if (IN == 1) {
;       float mo[4]; load4bf(M + grow * 1024 + gcol, mo);
;       v[0] += mo[0]; v[1] += mo[1]; v[2] += mo[2]; v[3] += mo[3];
;     }
;     if (IN == 2) {
;       float4 mo = *reinterpret_cast<const float4*>(macc + grow * 1024 + gcol);
;       v[0] += mo.x; v[1] += mo.y; v[2] += mo.z; v[3] += mo.w;
;     }
;     if (OUT == 1) *reinterpret_cast<float4*>(macc + grow * 1024 + gcol) = make_float4(v[0], v[1], v[2], v[3]);
	s_nop 0
	v_add_u32_e32 v8, s24, v91
	v_ashrrev_i32_e32 v6, 5, v8
	v_ashrrev_i32_e32 v7, 31, v6
	v_lshl_add_u64 v[10:11], s[46:47], 0, v[6:7]
	v_lshl_or_b32 v9, v6, 9, v152
	v_mov_b64_e32 v[6:7], s[44:45]
	v_mad_u64_u32 v[12:13], s[48:49], v10, s22, v[6:7]
	v_mad_i32_i24 v13, v11, s22, v13
	v_lshl_add_u64 v[12:13], v[12:13], 0, v[4:5]
	v_add_co_u32_e32 v12, vcc, 0x5000, v12
	s_addk_i32 s24, 0x800
	s_nop 0
	v_addc_co_u32_e32 v13, vcc, 0, v13, vcc
	v_mov_b32_e32 v12, v208
	v_mov_b32_e32 v13, v209
	s_cmpk_lg_i32 s24, 0x1000
	v_lshlrev_b32_e32 v14, 16, v12
	v_and_b32_e32 v12, 0xffff0000, v12
	v_lshlrev_b32_e32 v16, 16, v13
	v_mul_f32_e32 v12, 0xbfb8aa3b, v12
	v_and_b32_e32 v13, 0xffff0000, v13
	v_exp_f32_e32 v15, v12
	v_mul_f32_e32 v12, 0xbfb8aa3b, v16
	v_exp_f32_e32 v16, v12
	v_mul_f32_e32 v12, 0xbfb8aa3b, v13
	v_exp_f32_e32 v17, v12
	v_lshlrev_b64 v[12:13], 11, v[10:11]
	v_lshl_add_u64 v[12:13], v[0:1], 0, v[12:13]
	v_mov_b32_e32 v12, v210
	v_mov_b32_e32 v13, v211
	v_mul_f32_e32 v14, 0xbfb8aa3b, v14
	v_exp_f32_e32 v14, v14
	v_lshlrev_b64 v[10:11], 12, v[10:11]
	v_lshl_add_u64 v[22:23], v[2:3], 0, v[10:11]
	v_pk_add_f32 v[14:15], v[14:15], 1.0 op_sel_hi:[1,0]
	v_lshlrev_b32_e32 v18, 16, v12
	v_and_b32_e32 v19, 0xffff0000, v12
	v_lshlrev_b32_e32 v20, 16, v13
	v_and_b32_e32 v21, 0xffff0000, v13
	ds_read_b128 v[10:13], v9
	v_div_scale_f32 v9, s[48:49], v15, v15, 1.0
	v_rcp_f32_e32 v24, v9
	s_nop 0
	v_fma_f32 v25, -v9, v24, 1.0
	v_fmac_f32_e32 v24, v25, v24
	v_div_scale_f32 v25, vcc, 1.0, v15, 1.0
	v_mul_f32_e32 v26, v25, v24
	v_fma_f32 v27, -v9, v26, v25
	v_fmac_f32_e32 v26, v27, v24
	v_fma_f32 v9, -v9, v26, v25
	v_div_fmas_f32 v9, v9, v24, v26
	v_div_fixup_f32 v15, v9, v15, 1.0
	v_div_scale_f32 v9, s[48:49], v14, v14, 1.0
	v_rcp_f32_e32 v24, v9
	s_nop 0
	v_fma_f32 v25, -v9, v24, 1.0
	v_fmac_f32_e32 v24, v25, v24
	v_div_scale_f32 v25, vcc, 1.0, v14, 1.0
	v_mul_f32_e32 v26, v25, v24
	v_fma_f32 v27, -v9, v26, v25
	v_fmac_f32_e32 v26, v27, v24
	v_fma_f32 v9, -v9, v26, v25
	v_div_fmas_f32 v9, v9, v24, v26
	v_div_fixup_f32 v14, v9, v14, 1.0
	s_waitcnt lgkmcnt(0)
	v_pk_fma_f32 v[10:11], v[10:11], v[14:15], v[18:19]
	v_pk_add_f32 v[14:15], v[16:17], 1.0 op_sel_hi:[1,0]
	s_nop 0
	v_div_scale_f32 v9, s[48:49], v15, v15, 1.0
	v_rcp_f32_e32 v16, v9
	s_nop 0
	v_fma_f32 v17, -v9, v16, 1.0
	v_fmac_f32_e32 v16, v17, v16
	v_div_scale_f32 v17, vcc, 1.0, v15, 1.0
	v_mul_f32_e32 v18, v17, v16
	v_fma_f32 v19, -v9, v18, v17
	v_fmac_f32_e32 v18, v19, v16
	v_fma_f32 v9, -v9, v18, v17
	v_div_fmas_f32 v9, v9, v16, v18
	v_div_fixup_f32 v15, v9, v15, 1.0
	v_div_scale_f32 v9, s[48:49], v14, v14, 1.0
	v_rcp_f32_e32 v16, v9
	s_nop 0
	v_fma_f32 v17, -v9, v16, 1.0
	v_fmac_f32_e32 v16, v17, v16
	v_div_scale_f32 v17, vcc, 1.0, v14, 1.0
	v_mul_f32_e32 v18, v17, v16
	v_fma_f32 v19, -v9, v18, v17
	v_fmac_f32_e32 v18, v19, v16
	v_fma_f32 v9, -v9, v18, v17
	v_div_fmas_f32 v9, v9, v16, v18
	v_div_fixup_f32 v14, v9, v14, 1.0
	v_pk_fma_f32 v[12:13], v[12:13], v[14:15], v[20:21]
	v_add_u32_e32 v9, 0x100, v8
	global_store_dwordx4 v[22:23], v[10:13], off
	s_nop 1
	v_ashrrev_i32_e32 v10, 5, v9
	v_ashrrev_i32_e32 v11, 31, v10
	v_lshl_add_u64 v[12:13], s[46:47], 0, v[10:11]
	v_lshl_or_b32 v9, v10, 9, v152
	v_mad_u64_u32 v[10:11], s[48:49], v12, s22, v[6:7]
	v_mad_i32_i24 v11, v13, s22, v11
	v_lshl_add_u64 v[10:11], v[10:11], 0, v[4:5]
	v_add_co_u32_e32 v10, vcc, s21, v10
	s_nop 1
	v_addc_co_u32_e32 v11, vcc, 0, v11, vcc
	v_mov_b32_e32 v10, v212
	v_mov_b32_e32 v11, v213
	v_lshlrev_b32_e32 v14, 16, v10
	v_and_b32_e32 v10, 0xffff0000, v10
	v_lshlrev_b32_e32 v16, 16, v11
	v_mul_f32_e32 v10, 0xbfb8aa3b, v10
	v_and_b32_e32 v11, 0xffff0000, v11
	v_exp_f32_e32 v15, v10
	v_mul_f32_e32 v10, 0xbfb8aa3b, v16
	v_exp_f32_e32 v16, v10
	v_mul_f32_e32 v10, 0xbfb8aa3b, v11
	v_exp_f32_e32 v17, v10
	v_lshlrev_b64 v[10:11], 11, v[12:13]
	v_lshl_add_u64 v[10:11], v[0:1], 0, v[10:11]
	v_mov_b32_e32 v10, v214
	v_mov_b32_e32 v11, v215
	v_mul_f32_e32 v14, 0xbfb8aa3b, v14
	v_exp_f32_e32 v14, v14
	v_lshlrev_b32_e32 v18, 16, v10
	v_and_b32_e32 v19, 0xffff0000, v10
	v_lshlrev_b32_e32 v20, 16, v11
	v_and_b32_e32 v21, 0xffff0000, v11
	v_lshlrev_b64 v[10:11], 12, v[12:13]
	v_pk_add_f32 v[14:15], v[14:15], 1.0 op_sel_hi:[1,0]
	v_lshl_add_u64 v[22:23], v[2:3], 0, v[10:11]
	ds_read_b128 v[10:13], v9
	v_div_scale_f32 v9, s[48:49], v15, v15, 1.0
	v_rcp_f32_e32 v24, v9
	s_nop 0
	v_fma_f32 v25, -v9, v24, 1.0
	v_fmac_f32_e32 v24, v25, v24
	v_div_scale_f32 v25, vcc, 1.0, v15, 1.0
	v_mul_f32_e32 v26, v25, v24
	v_fma_f32 v27, -v9, v26, v25
	v_fmac_f32_e32 v26, v27, v24
	v_fma_f32 v9, -v9, v26, v25
	v_div_fmas_f32 v9, v9, v24, v26
	v_div_fixup_f32 v15, v9, v15, 1.0
	v_div_scale_f32 v9, s[48:49], v14, v14, 1.0
	v_rcp_f32_e32 v24, v9
	s_nop 0
	v_fma_f32 v25, -v9, v24, 1.0
	v_fmac_f32_e32 v24, v25, v24
	v_div_scale_f32 v25, vcc, 1.0, v14, 1.0
	v_mul_f32_e32 v26, v25, v24
	v_fma_f32 v27, -v9, v26, v25
	v_fmac_f32_e32 v26, v27, v24
	v_fma_f32 v9, -v9, v26, v25
	v_div_fmas_f32 v9, v9, v24, v26
	v_div_fixup_f32 v14, v9, v14, 1.0
	s_waitcnt lgkmcnt(0)
; DEVI float sigmoidf_(float x) { return 1.f / (1.f + __expf(-x)); }
; template <int BR, int IN, int OUT>
; DEVI void p6_branch(const Params& P, int pm, int pn, float* macc, char* smem, int tid) {
;     ...
;   for (int q = 0; q < 16; ++q) {
;     const int id = tid + 256 * q, row = id >> 5, c4 = id & 31;
;     const long grow = (long)pm * 128 + row;
;     const int gcol = pn * 128 + c4 * 4;
;     float4 a = *reinterpret_cast<const float4*>(T + row * 128 + c4 * 4);
;     float g[4];
;     load4bf(Z + grow * NCOL + (9 + BR) * 1024 + gcol, g);
;     float v[4] = {sigmoidf_(g[0]) * a.x, sigmoidf_(g[1]) * a.y, sigmoidf_(g[2]) * a.z, sigmoidf_(g[3]) * a.w};
;     if (IN == 1) {
;       float mo[4]; load4bf(M + grow * 1024 + gcol, mo);
;       v[0] += mo[0]; v[1] += mo[1]; v[2] += mo[2]; v[3] += mo[3];
;     }
;     if (IN == 2) {
;       float4 mo = *reinterpret_cast<const float4*>(macc + grow * 1024 + gcol);
;       v[0] += mo.x; v[1] += mo.y; v[2] += mo.z; v[3] += mo.w;
;     }
;     if (OUT == 1) *reinterpret_cast<float4*>(macc + grow * 1024 + gcol) = make_float4(v[0], v[1], v[2], v[3]);
	v_pk_fma_f32 v[10:11], v[10:11], v[14:15], v[18:19]
	v_pk_add_f32 v[14:15], v[16:17], 1.0 op_sel_hi:[1,0]
	s_nop 0
	v_div_scale_f32 v9, s[48:49], v15, v15, 1.0
	v_rcp_f32_e32 v16, v9
	s_nop 0
	v_fma_f32 v17, -v9, v16, 1.0
	v_fmac_f32_e32 v16, v17, v16
	v_div_scale_f32 v17, vcc, 1.0, v15, 1.0
	v_mul_f32_e32 v18, v17, v16
	v_fma_f32 v19, -v9, v18, v17
	v_fmac_f32_e32 v18, v19, v16
	v_fma_f32 v9, -v9, v18, v17
	v_div_fmas_f32 v9, v9, v16, v18
	v_div_fixup_f32 v15, v9, v15, 1.0
	v_div_scale_f32 v9, s[48:49], v14, v14, 1.0
	v_rcp_f32_e32 v16, v9
	s_nop 0
	v_fma_f32 v17, -v9, v16, 1.0
	v_fmac_f32_e32 v16, v17, v16
	v_div_scale_f32 v17, vcc, 1.0, v14, 1.0
	v_mul_f32_e32 v18, v17, v16
	v_fma_f32 v19, -v9, v18, v17
	v_fmac_f32_e32 v18, v19, v16
	v_fma_f32 v9, -v9, v18, v17
	v_div_fmas_f32 v9, v9, v16, v18
	v_div_fixup_f32 v14, v9, v14, 1.0
	v_pk_fma_f32 v[12:13], v[12:13], v[14:15], v[20:21]
	v_add_u32_e32 v9, 0x200, v8
	global_store_dwordx4 v[22:23], v[10:13], off
	s_nop 1
	v_ashrrev_i32_e32 v10, 5, v9
	v_ashrrev_i32_e32 v11, 31, v10
	v_lshl_add_u64 v[12:13], s[46:47], 0, v[10:11]
	v_lshl_or_b32 v9, v10, 9, v152
	v_mad_u64_u32 v[10:11], s[48:49], v12, s22, v[6:7]
	v_mad_i32_i24 v11, v13, s22, v11
	v_lshl_add_u64 v[10:11], v[10:11], 0, v[4:5]
	v_add_co_u32_e32 v10, vcc, s21, v10
	s_nop 1
	v_addc_co_u32_e32 v11, vcc, 0, v11, vcc
	v_mov_b32_e32 v10, v216
	v_mov_b32_e32 v11, v217
	v_lshlrev_b32_e32 v14, 16, v10
	v_and_b32_e32 v10, 0xffff0000, v10
	v_lshlrev_b32_e32 v16, 16, v11
	v_mul_f32_e32 v10, 0xbfb8aa3b, v10
	v_and_b32_e32 v11, 0xffff0000, v11
	v_exp_f32_e32 v15, v10
	v_mul_f32_e32 v10, 0xbfb8aa3b, v16
	v_exp_f32_e32 v16, v10
	v_mul_f32_e32 v10, 0xbfb8aa3b, v11
	v_exp_f32_e32 v17, v10
	v_lshlrev_b64 v[10:11], 11, v[12:13]
	v_lshl_add_u64 v[10:11], v[0:1], 0, v[10:11]
	v_mov_b32_e32 v10, v218
	v_mov_b32_e32 v11, v219
	v_mul_f32_e32 v14, 0xbfb8aa3b, v14
	v_exp_f32_e32 v14, v14
	v_lshlrev_b32_e32 v18, 16, v10
	v_and_b32_e32 v19, 0xffff0000, v10
	v_lshlrev_b32_e32 v20, 16, v11
	v_and_b32_e32 v21, 0xffff0000, v11
	v_lshlrev_b64 v[10:11], 12, v[12:13]
	v_pk_add_f32 v[14:15], v[14:15], 1.0 op_sel_hi:[1,0]
	v_lshl_add_u64 v[22:23], v[2:3], 0, v[10:11]
	ds_read_b128 v[10:13], v9
	v_div_scale_f32 v9, s[48:49], v15, v15, 1.0
	v_rcp_f32_e32 v24, v9
	s_nop 0
	v_fma_f32 v25, -v9, v24, 1.0
	v_fmac_f32_e32 v24, v25, v24
	v_div_scale_f32 v25, vcc, 1.0, v15, 1.0
	v_mul_f32_e32 v26, v25, v24
	v_fma_f32 v27, -v9, v26, v25
	v_fmac_f32_e32 v26, v27, v24
	v_fma_f32 v9, -v9, v26, v25
	v_div_fmas_f32 v9, v9, v24, v26
	v_div_fixup_f32 v15, v9, v15, 1.0
	v_div_scale_f32 v9, s[48:49], v14, v14, 1.0
	v_rcp_f32_e32 v24, v9
	s_nop 0
	v_fma_f32 v25, -v9, v24, 1.0
	v_fmac_f32_e32 v24, v25, v24
	v_div_scale_f32 v25, vcc, 1.0, v14, 1.0
	v_mul_f32_e32 v26, v25, v24
	v_fma_f32 v27, -v9, v26, v25
	v_fmac_f32_e32 v26, v27, v24
	v_fma_f32 v9, -v9, v26, v25
	v_div_fmas_f32 v9, v9, v24, v26
	v_div_fixup_f32 v14, v9, v14, 1.0
	s_waitcnt lgkmcnt(0)
	v_pk_fma_f32 v[10:11], v[10:11], v[14:15], v[18:19]
	v_pk_add_f32 v[14:15], v[16:17], 1.0 op_sel_hi:[1,0]
	s_nop 0
	v_div_scale_f32 v9, s[48:49], v15, v15, 1.0
	v_rcp_f32_e32 v16, v9
	s_nop 0
	v_fma_f32 v17, -v9, v16, 1.0
	v_fmac_f32_e32 v16, v17, v16
	v_div_scale_f32 v17, vcc, 1.0, v15, 1.0
	v_mul_f32_e32 v18, v17, v16
	v_fma_f32 v19, -v9, v18, v17
	v_fmac_f32_e32 v18, v19, v16
	v_fma_f32 v9, -v9, v18, v17
	v_div_fmas_f32 v9, v9, v16, v18
	v_div_fixup_f32 v15, v9, v15, 1.0
	v_div_scale_f32 v9, s[48:49], v14, v14, 1.0
	v_rcp_f32_e32 v16, v9
	s_nop 0
	v_fma_f32 v17, -v9, v16, 1.0
	v_fmac_f32_e32 v16, v17, v16
	v_div_scale_f32 v17, vcc, 1.0, v14, 1.0
	v_mul_f32_e32 v18, v17, v16
	v_fma_f32 v19, -v9, v18, v17
	v_fmac_f32_e32 v18, v19, v16
	v_fma_f32 v9, -v9, v18, v17
	v_div_fmas_f32 v9, v9, v16, v18
	v_div_fixup_f32 v14, v9, v14, 1.0
	v_pk_fma_f32 v[12:13], v[12:13], v[14:15], v[20:21]
	v_add_u32_e32 v9, 0x300, v8
	global_store_dwordx4 v[22:23], v[10:13], off
	s_nop 1
	v_ashrrev_i32_e32 v10, 5, v9
	v_ashrrev_i32_e32 v11, 31, v10
	v_lshl_add_u64 v[12:13], s[46:47], 0, v[10:11]
	v_lshl_or_b32 v9, v10, 9, v152
	v_mad_u64_u32 v[10:11], s[48:49], v12, s22, v[6:7]
	v_mad_i32_i24 v11, v13, s22, v11
	v_lshl_add_u64 v[10:11], v[10:11], 0, v[4:5]
	v_add_co_u32_e32 v10, vcc, s21, v10
	s_nop 1
	v_addc_co_u32_e32 v11, vcc, 0, v11, vcc
	v_mov_b32_e32 v10, v220
	v_mov_b32_e32 v11, v221
	v_lshlrev_b32_e32 v14, 16, v10
	v_and_b32_e32 v10, 0xffff0000, v10
	v_lshlrev_b32_e32 v16, 16, v11
	v_mul_f32_e32 v10, 0xbfb8aa3b, v10
	v_and_b32_e32 v11, 0xffff0000, v11
	v_exp_f32_e32 v15, v10
	v_mul_f32_e32 v10, 0xbfb8aa3b, v16
	v_exp_f32_e32 v16, v10
	v_mul_f32_e32 v10, 0xbfb8aa3b, v11
	v_exp_f32_e32 v17, v10
	v_lshlrev_b64 v[10:11], 11, v[12:13]
	v_lshl_add_u64 v[10:11], v[0:1], 0, v[10:11]
	v_mov_b32_e32 v10, v222
	v_mov_b32_e32 v11, v223
	v_mul_f32_e32 v14, 0xbfb8aa3b, v14
	v_exp_f32_e32 v14, v14
	v_lshlrev_b32_e32 v18, 16, v10
	v_and_b32_e32 v19, 0xffff0000, v10
	v_lshlrev_b32_e32 v20, 16, v11
	v_and_b32_e32 v21, 0xffff0000, v11
	v_lshlrev_b64 v[10:11], 12, v[12:13]
	v_pk_add_f32 v[14:15], v[14:15], 1.0 op_sel_hi:[1,0]
	v_lshl_add_u64 v[22:23], v[2:3], 0, v[10:11]
	ds_read_b128 v[10:13], v9
	v_div_scale_f32 v9, s[48:49], v15, v15, 1.0
	v_rcp_f32_e32 v24, v9
	s_nop 0
	v_fma_f32 v25, -v9, v24, 1.0
	v_fmac_f32_e32 v24, v25, v24
	v_div_scale_f32 v25, vcc, 1.0, v15, 1.0
	v_mul_f32_e32 v26, v25, v24
	v_fma_f32 v27, -v9, v26, v25
	v_fmac_f32_e32 v26, v27, v24
	v_fma_f32 v9, -v9, v26, v25
	v_div_fmas_f32 v9, v9, v24, v26
	v_div_fixup_f32 v15, v9, v15, 1.0
	v_div_scale_f32 v9, s[48:49], v14, v14, 1.0
	v_rcp_f32_e32 v24, v9
	s_nop 0
	v_fma_f32 v25, -v9, v24, 1.0
	v_fmac_f32_e32 v24, v25, v24
	v_div_scale_f32 v25, vcc, 1.0, v14, 1.0
	v_mul_f32_e32 v26, v25, v24
	v_fma_f32 v27, -v9, v26, v25
	v_fmac_f32_e32 v26, v27, v24
	v_fma_f32 v9, -v9, v26, v25
	v_div_fmas_f32 v9, v9, v24, v26
	v_div_fixup_f32 v14, v9, v14, 1.0
	s_waitcnt lgkmcnt(0)
; DEVI float sigmoidf_(float x) { return 1.f / (1.f + __expf(-x)); }
; template <int BR, int IN, int OUT>
; DEVI void p6_branch(const Params& P, int pm, int pn, float* macc, char* smem, int tid) {
;     ...
; #pragma unroll 8
;   for (int q = 0; q < 16; ++q) {
;     const int id = tid + 256 * q, row = id >> 5, c4 = id & 31;
;     const long grow = (long)pm * 128 + row;
;     const int gcol = pn * 128 + c4 * 4;
;     float4 a = *reinterpret_cast<const float4*>(T + row * 128 + c4 * 4);
;     float g[4];
;     load4bf(Z + grow * NCOL + (9 + BR) * 1024 + gcol, g);
;     float v[4] = {sigmoidf_(g[0]) * a.x, sigmoidf_(g[1]) * a.y, sigmoidf_(g[2]) * a.z, sigmoidf_(g[3]) * a.w};
;     if (IN == 1) {
;       float mo[4]; load4bf(M + grow * 1024 + gcol, mo);
;       v[0] += mo[0]; v[1] += mo[1]; v[2] += mo[2]; v[3] += mo[3];
;     }
;     if (IN == 2) {
;       float4 mo = *reinterpret_cast<const float4*>(macc + grow * 1024 + gcol);
;       v[0] += mo.x; v[1] += mo.y; v[2] += mo.z; v[3] += mo.w;
;     }
;     if (OUT == 1) *reinterpret_cast<float4*>(macc + grow * 1024 + gcol) = make_float4(v[0], v[1], v[2], v[3]);
;     else store4bf(M + grow * 1024 + gcol, v);
;   }
	v_pk_fma_f32 v[10:11], v[10:11], v[14:15], v[18:19]
	v_pk_add_f32 v[14:15], v[16:17], 1.0 op_sel_hi:[1,0]
	s_nop 0
	v_div_scale_f32 v9, s[48:49], v15, v15, 1.0
	v_rcp_f32_e32 v16, v9
	s_nop 0
	v_fma_f32 v17, -v9, v16, 1.0
	v_fmac_f32_e32 v16, v17, v16
	v_div_scale_f32 v17, vcc, 1.0, v15, 1.0
	v_mul_f32_e32 v18, v17, v16
	v_fma_f32 v19, -v9, v18, v17
	v_fmac_f32_e32 v18, v19, v16
	v_fma_f32 v9, -v9, v18, v17
	v_div_fmas_f32 v9, v9, v16, v18
	v_div_fixup_f32 v15, v9, v15, 1.0
	v_div_scale_f32 v9, s[48:49], v14, v14, 1.0
	v_rcp_f32_e32 v16, v9
	s_nop 0
	v_fma_f32 v17, -v9, v16, 1.0
	v_fmac_f32_e32 v16, v17, v16
	v_div_scale_f32 v17, vcc, 1.0, v14, 1.0
	v_mul_f32_e32 v18, v17, v16
	v_fma_f32 v19, -v9, v18, v17
	v_fmac_f32_e32 v18, v19, v16
	v_fma_f32 v9, -v9, v18, v17
	v_div_fmas_f32 v9, v9, v16, v18
	v_div_fixup_f32 v14, v9, v14, 1.0
	v_pk_fma_f32 v[12:13], v[12:13], v[14:15], v[20:21]
	v_add_u32_e32 v9, 0x400, v8
	global_store_dwordx4 v[22:23], v[10:13], off
	s_nop 1
	v_ashrrev_i32_e32 v10, 5, v9
	v_ashrrev_i32_e32 v11, 31, v10
	v_lshl_add_u64 v[12:13], s[46:47], 0, v[10:11]
	v_lshl_or_b32 v9, v10, 9, v152
	v_mad_u64_u32 v[10:11], s[48:49], v12, s22, v[6:7]
	v_mad_i32_i24 v11, v13, s22, v11
	v_lshl_add_u64 v[10:11], v[10:11], 0, v[4:5]
	v_add_co_u32_e32 v10, vcc, s21, v10
	s_nop 1
	v_addc_co_u32_e32 v11, vcc, 0, v11, vcc
	v_mov_b32_e32 v10, v224
	v_mov_b32_e32 v11, v225
	v_lshlrev_b32_e32 v14, 16, v10
	v_and_b32_e32 v10, 0xffff0000, v10
	v_lshlrev_b32_e32 v16, 16, v11
	v_mul_f32_e32 v10, 0xbfb8aa3b, v10
	v_and_b32_e32 v11, 0xffff0000, v11
	v_exp_f32_e32 v15, v10
	v_mul_f32_e32 v10, 0xbfb8aa3b, v16
	v_exp_f32_e32 v16, v10
	v_mul_f32_e32 v10, 0xbfb8aa3b, v11
	v_exp_f32_e32 v17, v10
	v_lshlrev_b64 v[10:11], 11, v[12:13]
	v_lshl_add_u64 v[10:11], v[0:1], 0, v[10:11]
	v_mov_b32_e32 v10, v226
	v_mov_b32_e32 v11, v227
	v_mul_f32_e32 v14, 0xbfb8aa3b, v14
	v_exp_f32_e32 v14, v14
	v_lshlrev_b32_e32 v18, 16, v10
	v_and_b32_e32 v19, 0xffff0000, v10
	v_lshlrev_b32_e32 v20, 16, v11
	v_and_b32_e32 v21, 0xffff0000, v11
	v_lshlrev_b64 v[10:11], 12, v[12:13]
	v_pk_add_f32 v[14:15], v[14:15], 1.0 op_sel_hi:[1,0]
	v_lshl_add_u64 v[22:23], v[2:3], 0, v[10:11]
	ds_read_b128 v[10:13], v9
	v_div_scale_f32 v9, s[48:49], v15, v15, 1.0
	v_rcp_f32_e32 v24, v9
	s_nop 0
	v_fma_f32 v25, -v9, v24, 1.0
	v_fmac_f32_e32 v24, v25, v24
	v_div_scale_f32 v25, vcc, 1.0, v15, 1.0
	v_mul_f32_e32 v26, v25, v24
	v_fma_f32 v27, -v9, v26, v25
	v_fmac_f32_e32 v26, v27, v24
	v_fma_f32 v9, -v9, v26, v25
	v_div_fmas_f32 v9, v9, v24, v26
	v_div_fixup_f32 v15, v9, v15, 1.0
	v_div_scale_f32 v9, s[48:49], v14, v14, 1.0
	v_rcp_f32_e32 v24, v9
	s_nop 0
	v_fma_f32 v25, -v9, v24, 1.0
	v_fmac_f32_e32 v24, v25, v24
	v_div_scale_f32 v25, vcc, 1.0, v14, 1.0
	v_mul_f32_e32 v26, v25, v24
	v_fma_f32 v27, -v9, v26, v25
	v_fmac_f32_e32 v26, v27, v24
	v_fma_f32 v9, -v9, v26, v25
	v_div_fmas_f32 v9, v9, v24, v26
	v_div_fixup_f32 v14, v9, v14, 1.0
	s_waitcnt lgkmcnt(0)
	v_pk_fma_f32 v[10:11], v[10:11], v[14:15], v[18:19]
	v_pk_add_f32 v[14:15], v[16:17], 1.0 op_sel_hi:[1,0]
	s_nop 0
	v_div_scale_f32 v9, s[48:49], v15, v15, 1.0
	v_rcp_f32_e32 v16, v9
	s_nop 0
	v_fma_f32 v17, -v9, v16, 1.0
	v_fmac_f32_e32 v16, v17, v16
	v_div_scale_f32 v17, vcc, 1.0, v15, 1.0
	v_mul_f32_e32 v18, v17, v16
	v_fma_f32 v19, -v9, v18, v17
	v_fmac_f32_e32 v18, v19, v16
	v_fma_f32 v9, -v9, v18, v17
	v_div_fmas_f32 v9, v9, v16, v18
	v_div_fixup_f32 v15, v9, v15, 1.0
	v_div_scale_f32 v9, s[48:49], v14, v14, 1.0
	v_rcp_f32_e32 v16, v9
	s_nop 0
	v_fma_f32 v17, -v9, v16, 1.0
	v_fmac_f32_e32 v16, v17, v16
	v_div_scale_f32 v17, vcc, 1.0, v14, 1.0
	v_mul_f32_e32 v18, v17, v16
	v_fma_f32 v19, -v9, v18, v17
	v_fmac_f32_e32 v18, v19, v16
	v_fma_f32 v9, -v9, v18, v17
	v_div_fmas_f32 v9, v9, v16, v18
	v_div_fixup_f32 v14, v9, v14, 1.0
	v_pk_fma_f32 v[12:13], v[12:13], v[14:15], v[20:21]
	v_add_u32_e32 v9, 0x500, v8
	global_store_dwordx4 v[22:23], v[10:13], off
	s_nop 1
	v_ashrrev_i32_e32 v10, 5, v9
	v_ashrrev_i32_e32 v11, 31, v10
	v_lshl_add_u64 v[12:13], s[46:47], 0, v[10:11]
	v_lshl_or_b32 v9, v10, 9, v152
	v_mad_u64_u32 v[10:11], s[48:49], v12, s22, v[6:7]
	v_mad_i32_i24 v11, v13, s22, v11
	v_lshl_add_u64 v[10:11], v[10:11], 0, v[4:5]
	v_add_co_u32_e32 v10, vcc, s21, v10
	s_nop 1
	v_addc_co_u32_e32 v11, vcc, 0, v11, vcc
	v_mov_b32_e32 v10, v228
	v_mov_b32_e32 v11, v229
	v_lshlrev_b32_e32 v14, 16, v10
	v_and_b32_e32 v10, 0xffff0000, v10
	v_lshlrev_b32_e32 v16, 16, v11
	v_mul_f32_e32 v10, 0xbfb8aa3b, v10
	v_and_b32_e32 v11, 0xffff0000, v11
	v_exp_f32_e32 v15, v10
	v_mul_f32_e32 v10, 0xbfb8aa3b, v16
	v_exp_f32_e32 v16, v10
	v_mul_f32_e32 v10, 0xbfb8aa3b, v11
	v_exp_f32_e32 v17, v10
	v_lshlrev_b64 v[10:11], 11, v[12:13]
	v_lshl_add_u64 v[10:11], v[0:1], 0, v[10:11]
	v_mov_b32_e32 v10, v230
	v_mov_b32_e32 v11, v231
	v_mul_f32_e32 v14, 0xbfb8aa3b, v14
	v_exp_f32_e32 v14, v14
	v_lshlrev_b32_e32 v18, 16, v10
	v_and_b32_e32 v19, 0xffff0000, v10
	v_lshlrev_b32_e32 v20, 16, v11
	v_and_b32_e32 v21, 0xffff0000, v11
	v_lshlrev_b64 v[10:11], 12, v[12:13]
	v_pk_add_f32 v[14:15], v[14:15], 1.0 op_sel_hi:[1,0]
	v_lshl_add_u64 v[22:23], v[2:3], 0, v[10:11]
	ds_read_b128 v[10:13], v9
	v_div_scale_f32 v9, s[48:49], v15, v15, 1.0
	v_rcp_f32_e32 v24, v9
	s_nop 0
	v_fma_f32 v25, -v9, v24, 1.0
	v_fmac_f32_e32 v24, v25, v24
	v_div_scale_f32 v25, vcc, 1.0, v15, 1.0
	v_mul_f32_e32 v26, v25, v24
	v_fma_f32 v27, -v9, v26, v25
	v_fmac_f32_e32 v26, v27, v24
	v_fma_f32 v9, -v9, v26, v25
	v_div_fmas_f32 v9, v9, v24, v26
	v_div_fixup_f32 v15, v9, v15, 1.0
	v_div_scale_f32 v9, s[48:49], v14, v14, 1.0
	v_rcp_f32_e32 v24, v9
	s_nop 0
	v_fma_f32 v25, -v9, v24, 1.0
	v_fmac_f32_e32 v24, v25, v24
	v_div_scale_f32 v25, vcc, 1.0, v14, 1.0
	v_mul_f32_e32 v26, v25, v24
	v_fma_f32 v27, -v9, v26, v25
	v_fmac_f32_e32 v26, v27, v24
	v_fma_f32 v9, -v9, v26, v25
	v_div_fmas_f32 v9, v9, v24, v26
	v_div_fixup_f32 v14, v9, v14, 1.0
	s_waitcnt lgkmcnt(0)
; DEVI float sigmoidf_(float x) { return 1.f / (1.f + __expf(-x)); }
; template <int BR, int IN, int OUT>
; DEVI void p6_branch(const Params& P, int pm, int pn, float* macc, char* smem, int tid) {
;     ...
; #pragma unroll 8
;   for (int q = 0; q < 16; ++q) {
;     const int id = tid + 256 * q, row = id >> 5, c4 = id & 31;
;     const long grow = (long)pm * 128 + row;
;     const int gcol = pn * 128 + c4 * 4;
;     float4 a = *reinterpret_cast<const float4*>(T + row * 128 + c4 * 4);
;     float g[4];
;     load4bf(Z + grow * NCOL + (9 + BR) * 1024 + gcol, g);
;     float v[4] = {sigmoidf_(g[0]) * a.x, sigmoidf_(g[1]) * a.y, sigmoidf_(g[2]) * a.z, sigmoidf_(g[3]) * a.w};
;     if (IN == 1) {
;       float mo[4]; load4bf(M + grow * 1024 + gcol, mo);
;       v[0] += mo[0]; v[1] += mo[1]; v[2] += mo[2]; v[3] += mo[3];
;     }
;     if (IN == 2) {
;       float4 mo = *reinterpret_cast<const float4*>(macc + grow * 1024 + gcol);
;       v[0] += mo.x; v[1] += mo.y; v[2] += mo.z; v[3] += mo.w;
;     }
;     if (OUT == 1) *reinterpret_cast<float4*>(macc + grow * 1024 + gcol) = make_float4(v[0], v[1], v[2], v[3]);
;     else store4bf(M + grow * 1024 + gcol, v);
;   }
	v_pk_fma_f32 v[10:11], v[10:11], v[14:15], v[18:19]
	v_pk_add_f32 v[14:15], v[16:17], 1.0 op_sel_hi:[1,0]
	s_nop 0
	v_div_scale_f32 v9, s[48:49], v15, v15, 1.0
	v_rcp_f32_e32 v16, v9
	s_nop 0
	v_fma_f32 v17, -v9, v16, 1.0
	v_fmac_f32_e32 v16, v17, v16
	v_div_scale_f32 v17, vcc, 1.0, v15, 1.0
	v_mul_f32_e32 v18, v17, v16
	v_fma_f32 v19, -v9, v18, v17
	v_fmac_f32_e32 v18, v19, v16
	v_fma_f32 v9, -v9, v18, v17
	v_div_fmas_f32 v9, v9, v16, v18
	v_div_fixup_f32 v15, v9, v15, 1.0
	v_div_scale_f32 v9, s[48:49], v14, v14, 1.0
	v_rcp_f32_e32 v16, v9
	s_nop 0
	v_fma_f32 v17, -v9, v16, 1.0
	v_fmac_f32_e32 v16, v17, v16
	v_div_scale_f32 v17, vcc, 1.0, v14, 1.0
	v_mul_f32_e32 v18, v17, v16
	v_fma_f32 v19, -v9, v18, v17
	v_fmac_f32_e32 v18, v19, v16
	v_fma_f32 v9, -v9, v18, v17
	v_div_fmas_f32 v9, v9, v16, v18
	v_div_fixup_f32 v14, v9, v14, 1.0
	v_pk_fma_f32 v[12:13], v[12:13], v[14:15], v[20:21]
	v_add_u32_e32 v9, 0x600, v8
	global_store_dwordx4 v[22:23], v[10:13], off
	v_add_u32_e32 v8, 0x700, v8
	v_ashrrev_i32_e32 v8, 5, v8
	v_ashrrev_i32_e32 v10, 5, v9
	v_ashrrev_i32_e32 v11, 31, v10
	v_lshl_add_u64 v[12:13], s[46:47], 0, v[10:11]
	v_lshl_or_b32 v9, v10, 9, v152
	v_mad_u64_u32 v[10:11], s[48:49], v12, s22, v[6:7]
	v_mad_i32_i24 v11, v13, s22, v11
	v_lshl_add_u64 v[10:11], v[10:11], 0, v[4:5]
	v_add_co_u32_e32 v10, vcc, s21, v10
	s_nop 1
	v_addc_co_u32_e32 v11, vcc, 0, v11, vcc
	v_mov_b32_e32 v10, v232
	v_mov_b32_e32 v11, v233
	v_lshlrev_b32_e32 v14, 16, v10
	v_and_b32_e32 v10, 0xffff0000, v10
	v_lshlrev_b32_e32 v16, 16, v11
	v_mul_f32_e32 v10, 0xbfb8aa3b, v10
	v_and_b32_e32 v11, 0xffff0000, v11
	v_exp_f32_e32 v15, v10
	v_mul_f32_e32 v10, 0xbfb8aa3b, v16
	v_exp_f32_e32 v16, v10
	v_mul_f32_e32 v10, 0xbfb8aa3b, v11
	v_exp_f32_e32 v17, v10
	v_lshlrev_b64 v[10:11], 11, v[12:13]
	v_lshl_add_u64 v[10:11], v[0:1], 0, v[10:11]
	v_mov_b32_e32 v10, v234
	v_mov_b32_e32 v11, v235
	v_mul_f32_e32 v14, 0xbfb8aa3b, v14
	v_exp_f32_e32 v14, v14
	v_lshlrev_b32_e32 v18, 16, v10
	v_and_b32_e32 v19, 0xffff0000, v10
	v_lshlrev_b32_e32 v20, 16, v11
	v_and_b32_e32 v21, 0xffff0000, v11
	v_lshlrev_b64 v[10:11], 12, v[12:13]
	v_pk_add_f32 v[14:15], v[14:15], 1.0 op_sel_hi:[1,0]
	v_lshl_add_u64 v[22:23], v[2:3], 0, v[10:11]
	ds_read_b128 v[10:13], v9
	v_div_scale_f32 v9, s[48:49], v15, v15, 1.0
	v_rcp_f32_e32 v24, v9
	s_nop 0
	v_fma_f32 v25, -v9, v24, 1.0
	v_fmac_f32_e32 v24, v25, v24
	v_div_scale_f32 v25, vcc, 1.0, v15, 1.0
	v_mul_f32_e32 v26, v25, v24
	v_fma_f32 v27, -v9, v26, v25
	v_fmac_f32_e32 v26, v27, v24
	v_fma_f32 v9, -v9, v26, v25
	v_div_fmas_f32 v9, v9, v24, v26
	v_div_fixup_f32 v15, v9, v15, 1.0
	v_div_scale_f32 v9, s[48:49], v14, v14, 1.0
	v_rcp_f32_e32 v24, v9
	s_nop 0
	v_fma_f32 v25, -v9, v24, 1.0
	v_fmac_f32_e32 v24, v25, v24
	v_div_scale_f32 v25, vcc, 1.0, v14, 1.0
	v_mul_f32_e32 v26, v25, v24
	v_fma_f32 v27, -v9, v26, v25
	v_fmac_f32_e32 v26, v27, v24
	v_fma_f32 v9, -v9, v26, v25
	v_div_fmas_f32 v9, v9, v24, v26
	v_div_fixup_f32 v14, v9, v14, 1.0
	s_waitcnt lgkmcnt(0)
	v_pk_fma_f32 v[10:11], v[10:11], v[14:15], v[18:19]
	v_pk_add_f32 v[14:15], v[16:17], 1.0 op_sel_hi:[1,0]
	s_nop 0
	v_div_scale_f32 v9, s[48:49], v15, v15, 1.0
	v_rcp_f32_e32 v16, v9
	s_nop 0
	v_fma_f32 v17, -v9, v16, 1.0
	v_fmac_f32_e32 v16, v17, v16
	v_div_scale_f32 v17, vcc, 1.0, v15, 1.0
	v_mul_f32_e32 v18, v17, v16
	v_fma_f32 v19, -v9, v18, v17
	v_fmac_f32_e32 v18, v19, v16
	v_fma_f32 v9, -v9, v18, v17
	v_div_fmas_f32 v9, v9, v16, v18
	v_div_fixup_f32 v15, v9, v15, 1.0
	v_div_scale_f32 v9, s[48:49], v14, v14, 1.0
	v_rcp_f32_e32 v16, v9
	s_nop 0
	v_fma_f32 v17, -v9, v16, 1.0
	v_fmac_f32_e32 v16, v17, v16
	v_div_scale_f32 v17, vcc, 1.0, v14, 1.0
	v_mul_f32_e32 v18, v17, v16
	v_fma_f32 v19, -v9, v18, v17
	v_fmac_f32_e32 v18, v19, v16
	v_fma_f32 v9, -v9, v18, v17
	v_div_fmas_f32 v9, v9, v16, v18
	v_div_fixup_f32 v14, v9, v14, 1.0
	v_pk_fma_f32 v[12:13], v[12:13], v[14:15], v[20:21]
	v_ashrrev_i32_e32 v9, 31, v8
	global_store_dwordx4 v[22:23], v[10:13], off
	s_nop 1
	v_lshl_add_u64 v[10:11], s[46:47], 0, v[8:9]
	v_mad_u64_u32 v[6:7], s[48:49], v10, s22, v[6:7]
	v_mad_i32_i24 v7, v11, s22, v7
	v_lshl_add_u64 v[6:7], v[6:7], 0, v[4:5]
	v_add_co_u32_e32 v6, vcc, s21, v6
	v_lshl_or_b32 v8, v8, 9, v152
	s_nop 0
	v_addc_co_u32_e32 v7, vcc, 0, v7, vcc
	v_mov_b32_e32 v6, v236
	v_mov_b32_e32 v7, v237
	v_lshlrev_b32_e32 v9, 16, v6
	v_and_b32_e32 v6, 0xffff0000, v6
	v_lshlrev_b32_e32 v14, 16, v7
	v_mul_f32_e32 v6, 0xbfb8aa3b, v6
	v_and_b32_e32 v7, 0xffff0000, v7
	v_exp_f32_e32 v13, v6
	v_mul_f32_e32 v6, 0xbfb8aa3b, v14
	v_exp_f32_e32 v14, v6
	v_mul_f32_e32 v6, 0xbfb8aa3b, v7
	v_exp_f32_e32 v15, v6
	v_lshlrev_b64 v[6:7], 11, v[10:11]
	v_lshl_add_u64 v[6:7], v[0:1], 0, v[6:7]
	v_mov_b32_e32 v6, v238
	v_mov_b32_e32 v7, v239
	v_mul_f32_e32 v9, 0xbfb8aa3b, v9
	v_exp_f32_e32 v12, v9
	v_lshlrev_b32_e32 v16, 16, v6
	v_pk_add_f32 v[12:13], v[12:13], 1.0 op_sel_hi:[1,0]
	v_and_b32_e32 v17, 0xffff0000, v6
	v_div_scale_f32 v20, s[48:49], v13, v13, 1.0
	v_rcp_f32_e32 v21, v20
	v_lshlrev_b32_e32 v18, 16, v7
	v_and_b32_e32 v19, 0xffff0000, v7
	v_lshlrev_b64 v[6:7], 12, v[10:11]
	v_fma_f32 v22, -v20, v21, 1.0
	v_fmac_f32_e32 v21, v22, v21
	v_div_scale_f32 v22, vcc, 1.0, v13, 1.0
	v_mul_f32_e32 v23, v22, v21
	v_fma_f32 v24, -v20, v23, v22
	v_fmac_f32_e32 v23, v24, v21
	v_fma_f32 v20, -v20, v23, v22
	v_div_fmas_f32 v20, v20, v21, v23
	v_div_fixup_f32 v13, v20, v13, 1.0
	v_div_scale_f32 v20, s[48:49], v12, v12, 1.0
	v_rcp_f32_e32 v21, v20
	v_lshl_add_u64 v[10:11], v[2:3], 0, v[6:7]
	ds_read_b128 v[6:9], v8
	v_fma_f32 v22, -v20, v21, 1.0
	v_fmac_f32_e32 v21, v22, v21
	v_div_scale_f32 v22, vcc, 1.0, v12, 1.0
	v_mul_f32_e32 v23, v22, v21
	v_fma_f32 v24, -v20, v23, v22
	v_fmac_f32_e32 v23, v24, v21
	v_fma_f32 v20, -v20, v23, v22
	v_div_fmas_f32 v20, v20, v21, v23
	v_div_fixup_f32 v12, v20, v12, 1.0
	s_waitcnt lgkmcnt(0)
	v_pk_fma_f32 v[6:7], v[6:7], v[12:13], v[16:17]
	v_pk_add_f32 v[12:13], v[14:15], 1.0 op_sel_hi:[1,0]
	s_nop 0
	v_div_scale_f32 v14, s[48:49], v13, v13, 1.0
	v_rcp_f32_e32 v15, v14
	s_nop 0
	v_fma_f32 v16, -v14, v15, 1.0
	v_fmac_f32_e32 v15, v16, v15
	v_div_scale_f32 v16, vcc, 1.0, v13, 1.0
	v_mul_f32_e32 v17, v16, v15
	v_fma_f32 v20, -v14, v17, v16
	v_fmac_f32_e32 v17, v20, v15
	v_fma_f32 v14, -v14, v17, v16
	v_div_fmas_f32 v14, v14, v15, v17
	v_div_fixup_f32 v13, v14, v13, 1.0
	v_div_scale_f32 v14, s[48:49], v12, v12, 1.0
	v_rcp_f32_e32 v15, v14
	s_nop 0
	v_fma_f32 v16, -v14, v15, 1.0
	v_fmac_f32_e32 v15, v16, v15
	v_div_scale_f32 v16, vcc, 1.0, v12, 1.0
	v_mul_f32_e32 v17, v16, v15
	v_fma_f32 v20, -v14, v17, v16
	v_fmac_f32_e32 v17, v20, v15
	v_fma_f32 v14, -v14, v17, v16
	v_div_fmas_f32 v14, v14, v15, v17
	v_div_fixup_f32 v12, v14, v12, 1.0
	v_pk_fma_f32 v[8:9], v[8:9], v[12:13], v[18:19]
	global_store_dwordx4 v[10:11], v[6:9], off
	s_cbranch_scc1 .LBB0_737
; DEVI char* wsp(const Params& P, size_t off) { asm volatile("" : "+s"(off)); return P.ws + off; }
; #define ZERO_ACC(a) _Pragma("unroll") for (int m_ = 0; m_ < 4; ++m_) _Pragma("unroll") for (int n_ = 0; n_ < 4; ++n_) a[m_][n_] = f32x4{0.f, 0.f, 0.f, 0.f}
; template <int GATE>
; DEVI void gemm_core_t(f32x4 (&acc)[4][4], const bfu* __restrict__ A, int lda,
;                     const bfu* __restrict__ B, int ldb, int K, char* smem, int tid, const bfu* __restrict__ B2 = nullptr) {
;   const int wid = tid >> 6, lane = tid & 63;
;   const int wr = wid >> 1, wc = wid & 1, fr = lane & 15, fq = lane >> 4;
;   const int nt = K >> 6;
;   __syncthreads();
;   stage_tile(A, lda, 0, smem, tid);
;   if (GATE) stage_tile_gate(B, B2, 0, smem + 16384, tid); else stage_tile(B, ldb, 0, smem + 16384, tid);
; template <int BR, int IN, int OUT>
; DEVI void p6_branch(const Params& P, int pm, int pn, float* macc, char* smem, int tid) {
;   asm volatile("" : "+s"(pm), "+s"(pn));
;   const bfu* Z = (const bfu*)wsp(P, O_Z);
;   bfu* M = (bfu*)wsp(P, O_CB);
;   const bfu* A = (const bfu*)wsp(P, BR == 0 ? O_UA : BR == 1 ? O_UB : O_UC) + (long)pm * 128 * 1024;
;   const bfu* B = (const bfu*)wsp(P, BR == 0 ? O_WOA : BR == 1 ? O_WOB : O_WOC) + (long)pn * 128 * 1024;
;   f32x4 acc[4][4]; ZERO_ACC(acc);
;   gemm_core(acc, A, 1024, B, 1024, 1024, smem, tid);
	v_readlane_b32 vcc_lo, v255, 1
	s_nop 0
	s_cmp_eq_u32 vcc_lo, 1
	s_cbranch_scc0 .Lp6_b_start
	s_waitcnt vmcnt(0)
	s_barrier
	buffer_wbl2 sc1
	s_waitcnt vmcnt(0)
	v_writelane_b32 v255, 0, 1
	s_add_i32 s46, s2, 0xfffffe00
	s_lshl_b32 s46, s46, 2
	s_add_u32 s46, s46, 0x1f089840
	s_add_u32 s46, s30, s46
	s_addc_u32 s47, s31, 0
	v_mov_b32_e32 v0, 1
	v_cmp_eq_u32_e32 vcc, 0, v91
	s_and_saveexec_b64 s[4:5], vcc
	global_atomic_add v89, v0, s[46:47]
	s_or_b64 exec, exec, s[4:5]
	s_waitcnt vmcnt(0)
	s_branch .Lp6_latch
.Lp6_b_start:
	s_mov_b64 exec, -1
	s_ashr_i32 s41, s40, 31
	s_ashr_i32 s27, s26, 31
	s_mov_b64 s[44:45], 0x8582000
	s_mov_b64 s[46:47], 0x17d02000
	s_mov_b64 s[48:49], 0x15c02000
	s_lshl_b64 s[50:51], s[40:41], 18
	s_lshl_b64 s[54:55], s[26:27], 18
	s_add_u32 s24, s30, s48
	s_addc_u32 s27, s31, s49
	s_add_u32 s56, s24, s50
	s_mov_b64 s[52:53], 0x1a00000
	s_addc_u32 s57, s27, s51
	s_add_u32 s24, s30, s52
	s_addc_u32 s27, s31, s53
	s_add_u32 s58, s24, s54
	v_lshl_add_u64 v[0:1], s[56:57], 0, v[116:117]
	v_readfirstlane_b32 s24, v101
	v_lshl_add_u64 v[0:1], v[0:1], 0, v[88:89]
	s_mov_b32 m0, s24
	s_barrier
	global_load_lds_dwordx4 v[0:1], off
	v_lshl_add_u64 v[0:1], s[56:57], 0, v[118:119]
	v_mov_b32_e32 v125, v89
	v_readfirstlane_b32 s24, v103
	v_lshl_add_u64 v[0:1], v[0:1], 0, v[124:125]
	s_mov_b32 m0, s24
	v_mov_b32_e32 v127, v89
	global_load_lds_dwordx4 v[0:1], off
	v_lshl_add_u64 v[0:1], s[56:57], 0, v[120:121]
	v_readfirstlane_b32 s24, v105
	v_lshl_add_u64 v[0:1], v[0:1], 0, v[126:127]
	s_mov_b32 m0, s24
	v_mov_b32_e32 v129, v89
	global_load_lds_dwordx4 v[0:1], off
	v_lshl_add_u64 v[0:1], s[56:57], 0, v[122:123]
	v_readfirstlane_b32 s24, v107
	s_addc_u32 s59, s27, s55
	v_lshl_add_u64 v[0:1], v[0:1], 0, v[128:129]
	s_mov_b32 m0, s24
	v_readfirstlane_b32 s24, v153
	global_load_lds_dwordx4 v[0:1], off
	v_lshl_add_u64 v[0:1], s[58:59], 0, v[116:117]
	v_lshl_add_u64 v[0:1], v[0:1], 0, v[88:89]
	s_mov_b32 m0, s24
	v_readfirstlane_b32 s24, v154
	global_load_lds_dwordx4 v[0:1], off
	v_lshl_add_u64 v[0:1], s[58:59], 0, v[118:119]
	v_lshl_add_u64 v[0:1], v[0:1], 0, v[124:125]
	s_mov_b32 m0, s24
	v_readfirstlane_b32 s24, v155
	global_load_lds_dwordx4 v[0:1], off
	v_lshl_add_u64 v[0:1], s[58:59], 0, v[120:121]
	v_lshl_add_u64 v[0:1], v[0:1], 0, v[126:127]
	s_mov_b32 m0, s24
	v_readfirstlane_b32 s24, v156
	global_load_lds_dwordx4 v[0:1], off
	v_lshl_add_u64 v[0:1], s[58:59], 0, v[122:123]
	v_lshl_add_u64 v[0:1], v[0:1], 0, v[128:129]
	s_mov_b32 m0, s24
	s_add_u32 s48, s48, s50
	global_load_lds_dwordx4 v[0:1], off
	s_addc_u32 s49, s49, s51
	v_lshl_add_u64 v[124:125], v[108:109], 0, s[48:49]
	v_lshl_add_u64 v[126:127], v[110:111], 0, s[48:49]
	v_lshl_add_u64 v[128:129], v[112:113], 0, s[48:49]
	v_lshl_add_u64 v[130:131], v[114:115], 0, s[48:49]
	s_add_u32 s48, s52, s54
	s_addc_u32 s49, s53, s55
	v_mov_b32_e32 v0, 0
	v_lshl_add_u64 v[132:133], v[108:109], 0, s[48:49]
	v_lshl_add_u64 v[134:135], v[110:111], 0, s[48:49]
	v_lshl_add_u64 v[136:137], v[112:113], 0, s[48:49]
	v_lshl_add_u64 v[138:139], v[114:115], 0, s[48:49]
	s_mov_b64 s[48:49], 0
	s_mov_b32 s24, 0x8000
	v_mov_b32_e32 v1, v0
	v_mov_b32_e32 v2, v0
	v_mov_b32_e32 v3, v0
	v_mov_b32_e32 v4, v0
	v_mov_b32_e32 v5, v0
	v_mov_b32_e32 v6, v0
	v_mov_b32_e32 v7, v0
	v_mov_b32_e32 v8, v0
	v_mov_b32_e32 v9, v0
	v_mov_b32_e32 v10, v0
	v_mov_b32_e32 v11, v0
	v_mov_b32_e32 v12, v0
	v_mov_b32_e32 v13, v0
	v_mov_b32_e32 v14, v0
	v_mov_b32_e32 v15, v0
	v_mov_b32_e32 v16, v0
	v_mov_b32_e32 v17, v0
	v_mov_b32_e32 v18, v0
	v_mov_b32_e32 v19, v0
	v_mov_b32_e32 v20, v0
	v_mov_b32_e32 v21, v0
	v_mov_b32_e32 v22, v0
	v_mov_b32_e32 v23, v0
	v_mov_b32_e32 v24, v0
	v_mov_b32_e32 v25, v0
	v_mov_b32_e32 v26, v0
	v_mov_b32_e32 v27, v0
	v_mov_b32_e32 v28, v0
	v_mov_b32_e32 v29, v0
	v_mov_b32_e32 v30, v0
	v_mov_b32_e32 v31, v0
	v_mov_b32_e32 v32, v0
	v_mov_b32_e32 v33, v0
	v_mov_b32_e32 v34, v0
	v_mov_b32_e32 v35, v0
	v_mov_b32_e32 v36, v0
	v_mov_b32_e32 v37, v0
	v_mov_b32_e32 v38, v0
	v_mov_b32_e32 v39, v0
	v_mov_b32_e32 v40, v0
	v_mov_b32_e32 v41, v0
	v_mov_b32_e32 v42, v0
	v_mov_b32_e32 v43, v0
	v_mov_b32_e32 v44, v0
	v_mov_b32_e32 v45, v0
	v_mov_b32_e32 v46, v0
	v_mov_b32_e32 v47, v0
	v_mov_b32_e32 v48, v0
	v_mov_b32_e32 v49, v0
	v_mov_b32_e32 v50, v0
	v_mov_b32_e32 v51, v0
	v_mov_b32_e32 v52, v0
	v_mov_b32_e32 v53, v0
	v_mov_b32_e32 v54, v0
	v_mov_b32_e32 v55, v0
	v_mov_b32_e32 v56, v0
	v_mov_b32_e32 v57, v0
	v_mov_b32_e32 v58, v0
	v_mov_b32_e32 v59, v0
	v_mov_b32_e32 v60, v0
	v_mov_b32_e32 v61, v0
	v_mov_b32_e32 v62, v0
	v_mov_b32_e32 v63, v0
; template <int GATE>
; DEVI void gemm_core_t(f32x4 (&acc)[4][4], const bfu* __restrict__ A, int lda,
;                     const bfu* __restrict__ B, int ldb, int K, char* smem, int tid, const bfu* __restrict__ B2 = nullptr) {
;     ...
;   for (int t = 0; t < nt; ++t) {
;     asm volatile("s_waitcnt vmcnt(0)" ::: "memory");
;     __syncthreads();
;     char* cur = smem + (t & 1) * 32768;
;     if (t + 1 < nt) {
;       char* nx = smem + ((t + 1) & 1) * 32768;
;       stage_tile(A, lda, (t + 1) * 64, nx, tid);
;       if (GATE) stage_tile_gate(B, B2, (t + 1) * 64, nx + 16384, tid); else stage_tile(B, ldb, (t + 1) * 64, nx + 16384, tid);
;     }
; #pragma unroll
;     for (int kk = 0; kk < 2; ++kk) {
;       bf16x8 af[4], bfr[4];
; #pragma unroll
;       for (int m = 0; m < 4; ++m) af[m] = ldfrag(cur, wr * 64 + m * 16 + fr, kk * 4 + fq);
; #pragma unroll
;       for (int n = 0; n < 4; ++n) bfr[n] = ldfrag(cur + 16384, wc * 64 + n * 16 + fr, kk * 4 + fq);
; #pragma unroll
;       for (int m = 0; m < 4; ++m)
; #pragma unroll
;         for (int n = 0; n < 4; ++n)
;           acc[m][n] = __builtin_amdgcn_mfma_f32_16x16x32_bf16(af[m], bfr[n], acc[m][n], 0, 0, 0);
;     }
.LBB0_739:
	s_add_i32 s27, s24, 0xffff8000
	s_and_b32 s50, s27, 0x8000
	s_and_b32 s27, s24, 0x8000
	v_add_u32_e32 v88, s27, v101
	v_add_u32_e32 v153, 0x1000, v88
	v_readfirstlane_b32 s51, v88
	v_lshl_add_u64 v[154:155], v[124:125], 0, s[48:49]
	s_mov_b32 m0, s51
	v_readfirstlane_b32 s51, v153
	v_add_u32_e32 v153, 0x2000, v88
	s_waitcnt vmcnt(0)
	s_waitcnt vmcnt(0) lgkmcnt(0)
	s_barrier
	global_load_lds_dwordx4 v[154:155], off
	v_lshl_add_u64 v[154:155], v[126:127], 0, s[48:49]
	s_mov_b32 m0, s51
	v_readfirstlane_b32 s51, v153
	v_add_u32_e32 v153, 0x3000, v88
	global_load_lds_dwordx4 v[154:155], off
	v_lshl_add_u64 v[154:155], v[128:129], 0, s[48:49]
	s_mov_b32 m0, s51
	v_readfirstlane_b32 s51, v153
	v_add_u32_e32 v153, 0x4000, v88
	global_load_lds_dwordx4 v[154:155], off
	v_lshl_add_u64 v[154:155], v[130:131], 0, s[48:49]
	s_mov_b32 m0, s51
	v_readfirstlane_b32 s51, v153
	v_add_u32_e32 v153, 0x5000, v88
	global_load_lds_dwordx4 v[154:155], off
	v_lshl_add_u64 v[154:155], v[132:133], 0, s[48:49]
	s_mov_b32 m0, s51
	v_readfirstlane_b32 s51, v153
	v_add_u32_e32 v153, 0x6000, v88
	global_load_lds_dwordx4 v[154:155], off
	v_lshl_add_u64 v[154:155], v[134:135], 0, s[48:49]
	s_mov_b32 m0, s51
	v_readfirstlane_b32 s51, v153
	v_add_u32_e32 v88, 0x7000, v88
	global_load_lds_dwordx4 v[154:155], off
	v_lshl_add_u64 v[154:155], v[136:137], 0, s[48:49]
	s_mov_b32 m0, s51
	v_readfirstlane_b32 s51, v88
	global_load_lds_dwordx4 v[154:155], off
	v_lshl_add_u64 v[154:155], v[138:139], 0, s[48:49]
	s_mov_b32 m0, s51
	v_or_b32_e32 v88, s50, v146
	global_load_lds_dwordx4 v[154:155], off
	v_add_u32_e32 v153, v88, v147
	v_add_u32_e32 v88, v88, v148
	ds_read_b128 v[158:161], v153
	ds_read_b128 v[162:165], v153 offset:2048
	ds_read_b128 v[166:169], v153 offset:4096
	ds_read_b128 v[170:173], v153 offset:6144
	ds_read_b128 v[174:177], v88 offset:16384
	ds_read_b128 v[178:181], v88 offset:18432
	ds_read_b128 v[196:199], v88 offset:20480
	ds_read_b128 v[200:203], v88 offset:22528
	v_or_b32_e32 v88, s50, v149
	v_add_u32_e32 v153, v88, v147
	v_add_u32_e32 v88, v88, v148
	s_waitcnt lgkmcnt(0)
	v_mfma_f32_16x16x32_bf16 v[60:63], v[158:161], v[174:177], v[60:63]
	s_add_u32 s48, s48, 0x80
	s_addc_u32 s49, s49, 0
	s_add_i32 s24, s24, 0x8000
	v_mfma_f32_16x16x32_bf16 v[56:59], v[158:161], v[178:181], v[56:59]
	s_cmpk_lg_i32 s48, 0x780
	v_mfma_f32_16x16x32_bf16 v[52:55], v[158:161], v[196:199], v[52:55]
	v_mfma_f32_16x16x32_bf16 v[48:51], v[158:161], v[200:203], v[48:51]
	v_mfma_f32_16x16x32_bf16 v[44:47], v[162:165], v[174:177], v[44:47]
	v_mfma_f32_16x16x32_bf16 v[40:43], v[162:165], v[178:181], v[40:43]
	v_mfma_f32_16x16x32_bf16 v[36:39], v[162:165], v[196:199], v[36:39]
	v_mfma_f32_16x16x32_bf16 v[32:35], v[162:165], v[200:203], v[32:35]
	v_mfma_f32_16x16x32_bf16 v[28:31], v[166:169], v[174:177], v[28:31]
	v_mfma_f32_16x16x32_bf16 v[24:27], v[166:169], v[178:181], v[24:27]
	v_mfma_f32_16x16x32_bf16 v[20:23], v[166:169], v[196:199], v[20:23]
	v_mfma_f32_16x16x32_bf16 v[16:19], v[166:169], v[200:203], v[16:19]
	v_mfma_f32_16x16x32_bf16 v[12:15], v[170:173], v[174:177], v[12:15]
	v_mfma_f32_16x16x32_bf16 v[8:11], v[170:173], v[178:181], v[8:11]
	v_mfma_f32_16x16x32_bf16 v[4:7], v[170:173], v[196:199], v[4:7]
	v_mfma_f32_16x16x32_bf16 v[0:3], v[170:173], v[200:203], v[0:3]
	ds_read_b128 v[158:161], v153
	ds_read_b128 v[162:165], v153 offset:2048
	ds_read_b128 v[166:169], v153 offset:4096
	ds_read_b128 v[170:173], v153 offset:6144
	ds_read_b128 v[174:177], v88 offset:16384
	ds_read_b128 v[178:181], v88 offset:18432
	ds_read_b128 v[196:199], v88 offset:20480
	ds_read_b128 v[200:203], v88 offset:22528
	s_waitcnt lgkmcnt(0)
	v_mfma_f32_16x16x32_bf16 v[60:63], v[158:161], v[174:177], v[60:63]
	v_mfma_f32_16x16x32_bf16 v[56:59], v[158:161], v[178:181], v[56:59]
	v_mfma_f32_16x16x32_bf16 v[52:55], v[158:161], v[196:199], v[52:55]
	v_mfma_f32_16x16x32_bf16 v[48:51], v[158:161], v[200:203], v[48:51]
	v_mfma_f32_16x16x32_bf16 v[44:47], v[162:165], v[174:177], v[44:47]
	v_mfma_f32_16x16x32_bf16 v[40:43], v[162:165], v[178:181], v[40:43]
	v_mfma_f32_16x16x32_bf16 v[36:39], v[162:165], v[196:199], v[36:39]
	v_mfma_f32_16x16x32_bf16 v[32:35], v[162:165], v[200:203], v[32:35]
	v_mfma_f32_16x16x32_bf16 v[28:31], v[166:169], v[174:177], v[28:31]
	v_mfma_f32_16x16x32_bf16 v[24:27], v[166:169], v[178:181], v[24:27]
	v_mfma_f32_16x16x32_bf16 v[20:23], v[166:169], v[196:199], v[20:23]
	v_mfma_f32_16x16x32_bf16 v[16:19], v[166:169], v[200:203], v[16:19]
	v_mfma_f32_16x16x32_bf16 v[12:15], v[170:173], v[174:177], v[12:15]
	v_mfma_f32_16x16x32_bf16 v[8:11], v[170:173], v[178:181], v[8:11]
	v_mfma_f32_16x16x32_bf16 v[4:7], v[170:173], v[196:199], v[4:7]
	v_mfma_f32_16x16x32_bf16 v[0:3], v[170:173], v[200:203], v[0:3]
	s_cbranch_scc1 .LBB0_739
	v_add_u32_e32 v88, s27, v146
	v_add_u32_e32 v153, v88, v147
	s_waitcnt vmcnt(0)
	s_waitcnt vmcnt(0)
	s_barrier
; template <int GATE>
; DEVI void gemm_core_t(f32x4 (&acc)[4][4], const bfu* __restrict__ A, int lda,
;                     const bfu* __restrict__ B, int ldb, int K, char* smem, int tid, const bfu* __restrict__ B2 = nullptr) {
;     ...
; #pragma unroll
;     for (int kk = 0; kk < 2; ++kk) {
;       bf16x8 af[4], bfr[4];
; #pragma unroll
;       for (int m = 0; m < 4; ++m) af[m] = ldfrag(cur, wr * 64 + m * 16 + fr, kk * 4 + fq);
; #pragma unroll
;       for (int n = 0; n < 4; ++n) bfr[n] = ldfrag(cur + 16384, wc * 64 + n * 16 + fr, kk * 4 + fq);
; #pragma unroll
;       for (int m = 0; m < 4; ++m)
; #pragma unroll
;         for (int n = 0; n < 4; ++n)
;           acc[m][n] = __builtin_amdgcn_mfma_f32_16x16x32_bf16(af[m], bfr[n], acc[m][n], 0, 0, 0);
;     }
; DEVI void epi_stage_f32(const f32x4 (&acc)[4][4], char* smem, int tid) {
;   const int wid = tid >> 6, lane = tid & 63, wr = wid >> 1, wc = wid & 1, fr = lane & 15, fq = lane >> 4;
;   float* T = reinterpret_cast<float*>(smem);
;   __syncthreads();
; #pragma unroll
;   for (int m = 0; m < 4; ++m)
; #pragma unroll
;     for (int n = 0; n < 4; ++n)
; #pragma unroll
;       for (int j = 0; j < 4; ++j)
;         T[(wr * 64 + m * 16 + fq * 4 + j) * 128 + wc * 64 + n * 16 + fr] = acc[m][n][j];
;   __syncthreads();
; }
	ds_read_b128 v[124:127], v153
	v_add_u32_e32 v88, v88, v148
	ds_read_b128 v[128:131], v88 offset:16384
	ds_read_b128 v[132:135], v153 offset:2048
	ds_read_b128 v[136:139], v88 offset:18432
	ds_read_b128 v[158:161], v88 offset:20480
	ds_read_b128 v[162:165], v88 offset:22528
	s_waitcnt lgkmcnt(3)
	v_mfma_f32_16x16x32_bf16 v[44:47], v[132:135], v[128:131], v[44:47]
	v_add_u32_e32 v88, s27, v149
	s_add_u32 s44, s30, s44
	s_addc_u32 s45, s31, s45
	v_mfma_f32_16x16x32_bf16 v[60:63], v[124:127], v[128:131], v[60:63]
	s_add_u32 s46, s30, s46
	s_addc_u32 s47, s31, s47
	s_lshl_b64 s[40:41], s[40:41], 7
	s_waitcnt lgkmcnt(2)
	v_mfma_f32_16x16x32_bf16 v[56:59], v[124:127], v[136:139], v[56:59]
	s_mov_b32 s24, 0
	s_waitcnt lgkmcnt(1)
	v_mfma_f32_16x16x32_bf16 v[52:55], v[124:127], v[158:161], v[52:55]
	s_waitcnt lgkmcnt(0)
	v_mfma_f32_16x16x32_bf16 v[48:51], v[124:127], v[162:165], v[48:51]
	v_mfma_f32_16x16x32_bf16 v[40:43], v[132:135], v[136:139], v[40:43]
	v_mfma_f32_16x16x32_bf16 v[36:39], v[132:135], v[158:161], v[36:39]
	v_mfma_f32_16x16x32_bf16 v[32:35], v[132:135], v[162:165], v[32:35]
	ds_read_b128 v[124:127], v153 offset:4096
	ds_read_b128 v[132:135], v153 offset:6144
	v_add_u32_e32 v153, v88, v147
	v_add_u32_e32 v88, v88, v148
	s_waitcnt lgkmcnt(1)
	v_mfma_f32_16x16x32_bf16 v[28:31], v[124:127], v[128:131], v[28:31]
	v_mfma_f32_16x16x32_bf16 v[24:27], v[124:127], v[136:139], v[24:27]
	v_mfma_f32_16x16x32_bf16 v[20:23], v[124:127], v[158:161], v[20:23]
	v_mfma_f32_16x16x32_bf16 v[16:19], v[124:127], v[162:165], v[16:19]
	ds_read_b128 v[124:127], v153
	s_waitcnt lgkmcnt(1)
	v_mfma_f32_16x16x32_bf16 v[12:15], v[132:135], v[128:131], v[12:15]
	v_mfma_f32_16x16x32_bf16 v[8:11], v[132:135], v[136:139], v[8:11]
	v_mfma_f32_16x16x32_bf16 v[4:7], v[132:135], v[158:161], v[4:7]
	v_mfma_f32_16x16x32_bf16 v[0:3], v[132:135], v[162:165], v[0:3]
	ds_read_b128 v[128:131], v88 offset:16384
	ds_read_b128 v[132:135], v153 offset:2048
	ds_read_b128 v[136:139], v88 offset:18432
	ds_read_b128 v[158:161], v88 offset:20480
	ds_read_b128 v[162:165], v88 offset:22528
	s_waitcnt lgkmcnt(4)
	v_mfma_f32_16x16x32_bf16 v[60:63], v[124:127], v[128:131], v[60:63]
	s_waitcnt lgkmcnt(2)
	v_mfma_f32_16x16x32_bf16 v[56:59], v[124:127], v[136:139], v[56:59]
	s_waitcnt lgkmcnt(1)
	v_mfma_f32_16x16x32_bf16 v[52:55], v[124:127], v[158:161], v[52:55]
	s_waitcnt lgkmcnt(0)
	v_mfma_f32_16x16x32_bf16 v[48:51], v[124:127], v[162:165], v[48:51]
	ds_read_b128 v[124:127], v153 offset:4096
	ds_read_b128 v[166:169], v153 offset:6144
	s_waitcnt lgkmcnt(0)
	s_barrier
	v_mfma_f32_16x16x32_bf16 v[44:47], v[132:135], v[128:131], v[44:47]
	ds_write2_b32 v150, v60, v56 offset1:16
	ds_write2_b32 v150, v61, v57 offset0:128 offset1:144
	ds_write2_b32 v140, v62, v58 offset1:16
	ds_write2_b32 v140, v63, v59 offset0:128 offset1:144
	v_mfma_f32_16x16x32_bf16 v[40:43], v[132:135], v[136:139], v[40:43]
	ds_write2_b32 v150, v52, v48 offset0:32 offset1:48
	ds_write2_b32 v150, v53, v49 offset0:160 offset1:176
	ds_write2_b32 v140, v54, v50 offset0:32 offset1:48
	ds_write2_b32 v140, v55, v51 offset0:160 offset1:176
	s_nop 3
	ds_write2_b32 v141, v44, v40 offset1:16
	ds_write2_b32 v141, v45, v41 offset0:128 offset1:144
	v_mfma_f32_16x16x32_bf16 v[36:39], v[132:135], v[158:161], v[36:39]
	v_mfma_f32_16x16x32_bf16 v[32:35], v[132:135], v[162:165], v[32:35]
	ds_write2_b32 v142, v46, v42 offset1:16
	ds_write2_b32 v142, v47, v43 offset0:128 offset1:144
	s_nop 5
	ds_write2_b32 v141, v36, v32 offset0:32 offset1:48
	ds_write2_b32 v141, v37, v33 offset0:160 offset1:176
	ds_write2_b32 v142, v38, v34 offset0:32 offset1:48
	ds_write2_b32 v142, v39, v35 offset0:160 offset1:176
	v_mfma_f32_16x16x32_bf16 v[28:31], v[124:127], v[128:131], v[28:31]
	v_mfma_f32_16x16x32_bf16 v[24:27], v[124:127], v[136:139], v[24:27]
	s_nop 7
	ds_write2_b32 v143, v28, v24 offset1:16
	ds_write2_b32 v143, v29, v25 offset0:128 offset1:144
	ds_write2_b32 v144, v30, v26 offset1:16
	v_mfma_f32_16x16x32_bf16 v[20:23], v[124:127], v[158:161], v[20:23]
	v_mfma_f32_16x16x32_bf16 v[16:19], v[124:127], v[162:165], v[16:19]
	ds_write2_b32 v144, v31, v27 offset0:128 offset1:144
	s_nop 6
	ds_write2_b32 v143, v20, v16 offset0:32 offset1:48
	ds_write2_b32 v143, v21, v17 offset0:160 offset1:176
	v_mfma_f32_16x16x32_bf16 v[12:15], v[166:169], v[128:131], v[12:15]
	v_mfma_f32_16x16x32_bf16 v[8:11], v[166:169], v[136:139], v[8:11]
	ds_write2_b32 v144, v22, v18 offset0:32 offset1:48
	ds_write2_b32 v144, v23, v19 offset0:160 offset1:176
	s_nop 5
	ds_write2_b32 v145, v12, v8 offset1:16
	ds_write2_b32 v145, v13, v9 offset0:128 offset1:144
	ds_write2_b32 v157, v14, v10 offset1:16
	ds_write2_b32 v157, v15, v11 offset0:128 offset1:144
	v_mfma_f32_16x16x32_bf16 v[4:7], v[166:169], v[158:161], v[4:7]
	v_mfma_f32_16x16x32_bf16 v[0:3], v[166:169], v[162:165], v[0:3]
	s_nop 7
	ds_write2_b32 v145, v4, v0 offset0:32 offset1:48
	ds_write2_b32 v145, v5, v1 offset0:160 offset1:176
	ds_write2_b32 v157, v6, v2 offset0:32 offset1:48
	ds_write2_b32 v157, v7, v3 offset0:160 offset1:176
	v_lshl_or_b32 v4, s26, 7, v151
	v_ashrrev_i32_e32 v5, 31, v4
	v_lshl_add_u64 v[0:1], v[4:5], 2, s[42:43]
	v_lshl_add_u64 v[2:3], v[4:5], 1, s[46:47]
	v_lshlrev_b64 v[4:5], 1, v[4:5]
	v_readlane_b32 vcc_lo, v255, 1
	s_nop 0
	s_cmp_eq_u32 vcc_lo, 2
	s_cbranch_scc0 .Lp6_nowait
	s_add_i32 s4, s2, 0xfffffe00
	s_lshl_b32 s4, s4, 2
	s_add_u32 s4, s4, 0x1f089840
	s_add_u32 s4, s30, s4
	s_addc_u32 s5, s31, 0
.Lp6_spin:
	global_load_dword v204, v89, s[4:5] sc1
	s_waitcnt vmcnt(0)
	v_readfirstlane_b32 vcc_lo, v204
	s_cmp_lg_u32 vcc_lo, 0
	s_cbranch_scc1 .Lp6_spin_done
	s_sleep 2
	s_branch .Lp6_spin
; DEVI float sigmoidf_(float x) { return 1.f / (1.f + __expf(-x)); }
; template <int BR, int IN, int OUT>
; DEVI void p6_branch(const Params& P, int pm, int pn, float* macc, char* smem, int tid) {
;     ...
; #pragma unroll 8
;   for (int q = 0; q < 16; ++q) {
;     const int id = tid + 256 * q, row = id >> 5, c4 = id & 31;
;     const long grow = (long)pm * 128 + row;
;     const int gcol = pn * 128 + c4 * 4;
;     float4 a = *reinterpret_cast<const float4*>(T + row * 128 + c4 * 4);
;     float g[4];
;     load4bf(Z + grow * NCOL + (9 + BR) * 1024 + gcol, g);
;     float v[4] = {sigmoidf_(g[0]) * a.x, sigmoidf_(g[1]) * a.y, sigmoidf_(g[2]) * a.z, sigmoidf_(g[3]) * a.w};
;     if (IN == 1) {
;       float mo[4]; load4bf(M + grow * 1024 + gcol, mo);
;       v[0] += mo[0]; v[1] += mo[1]; v[2] += mo[2]; v[3] += mo[3];
;     }
;     if (IN == 2) {
;       float4 mo = *reinterpret_cast<const float4*>(macc + grow * 1024 + gcol);
;       v[0] += mo.x; v[1] += mo.y; v[2] += mo.z; v[3] += mo.w;
.Lp6_spin_done:
	s_barrier
	global_store_dword v89, v89, s[4:5]
	buffer_inv sc1
.Lp6_nowait:
	s_waitcnt lgkmcnt(0)
	s_barrier
.LBB0_741:
	v_add_u32_e32 v238, s24, v91
	v_ashrrev_i32_e32 v236, 5, v238
	v_ashrrev_i32_e32 v237, 31, v236
	v_lshl_add_u64 v[240:241], s[40:41], 0, v[236:237]
	v_mov_b64_e32 v[236:237], s[44:45]
	v_mad_u64_u32 v[242:243], s[26:27], v240, s22, v[236:237]
	v_mad_i32_i24 v243, v241, s22, v243
	v_lshl_add_u64 v[242:243], v[242:243], 0, v[4:5]
	v_add_co_u32_e32 v242, vcc, 0x5000, v242
	s_nop 1
	v_addc_co_u32_e32 v243, vcc, 0, v243, vcc
	global_load_dwordx2 v[154:155], v[242:243], off
	v_add_u32_e32 v238, s24, v91
	v_ashrrev_i32_e32 v236, 5, v238
	v_ashrrev_i32_e32 v237, 31, v236
	v_lshl_add_u64 v[240:241], s[40:41], 0, v[236:237]
	v_lshlrev_b64 v[242:243], 12, v[240:241]
	v_lshl_add_u64 v[244:245], v[0:1], 0, v[242:243]
	global_load_dwordx4 v[156:159], v[244:245], off
	v_add_u32_e32 v238, s24, v91
	v_mov_b64_e32 v[236:237], s[44:45]
	v_add_u32_e32 v239, 0x100, v238
	v_ashrrev_i32_e32 v240, 5, v239
	v_ashrrev_i32_e32 v241, 31, v240
	v_lshl_add_u64 v[242:243], s[40:41], 0, v[240:241]
	v_mad_u64_u32 v[240:241], s[26:27], v242, s22, v[236:237]
	v_mad_i32_i24 v241, v243, s22, v241
	v_lshl_add_u64 v[240:241], v[240:241], 0, v[4:5]
	v_add_co_u32_e32 v240, vcc, s21, v240
	s_nop 1
	v_addc_co_u32_e32 v241, vcc, 0, v241, vcc
	global_load_dwordx2 v[160:161], v[240:241], off
	v_add_u32_e32 v236, s24, v91
	v_add_u32_e32 v237, 0x100, v236
	v_ashrrev_i32_e32 v238, 5, v237
	v_ashrrev_i32_e32 v239, 31, v238
	v_lshl_add_u64 v[240:241], s[40:41], 0, v[238:239]
	v_lshlrev_b64 v[238:239], 12, v[240:241]
	v_lshl_add_u64 v[242:243], v[0:1], 0, v[238:239]
	global_load_dwordx4 v[164:167], v[242:243], off
	v_add_u32_e32 v238, s24, v91
	v_mov_b64_e32 v[236:237], s[44:45]
	v_add_u32_e32 v239, 0x200, v238
	v_ashrrev_i32_e32 v240, 5, v239
	v_ashrrev_i32_e32 v241, 31, v240
	v_lshl_add_u64 v[242:243], s[40:41], 0, v[240:241]
	v_mad_u64_u32 v[240:241], s[26:27], v242, s22, v[236:237]
	v_mad_i32_i24 v241, v243, s22, v241
	v_lshl_add_u64 v[240:241], v[240:241], 0, v[4:5]
	v_add_co_u32_e32 v240, vcc, s21, v240
	s_nop 1
	v_addc_co_u32_e32 v241, vcc, 0, v241, vcc
	global_load_dwordx2 v[162:163], v[240:241], off
	v_add_u32_e32 v236, s24, v91
	v_add_u32_e32 v237, 0x200, v236
	v_ashrrev_i32_e32 v238, 5, v237
	v_ashrrev_i32_e32 v239, 31, v238
	v_lshl_add_u64 v[240:241], s[40:41], 0, v[238:239]
	v_lshlrev_b64 v[238:239], 12, v[240:241]
	v_lshl_add_u64 v[242:243], v[0:1], 0, v[238:239]
	global_load_dwordx4 v[168:171], v[242:243], off
	v_add_u32_e32 v238, s24, v91
	v_mov_b64_e32 v[236:237], s[44:45]
	v_add_u32_e32 v239, 0x300, v238
	v_ashrrev_i32_e32 v240, 5, v239
	v_ashrrev_i32_e32 v241, 31, v240
	v_lshl_add_u64 v[242:243], s[40:41], 0, v[240:241]
	v_mad_u64_u32 v[240:241], s[26:27], v242, s22, v[236:237]
	v_mad_i32_i24 v241, v243, s22, v241
	v_lshl_add_u64 v[240:241], v[240:241], 0, v[4:5]
	v_add_co_u32_e32 v240, vcc, s21, v240
	s_nop 1
	v_addc_co_u32_e32 v241, vcc, 0, v241, vcc
	global_load_dwordx2 v[172:173], v[240:241], off
	v_add_u32_e32 v236, s24, v91
	v_add_u32_e32 v237, 0x300, v236
	v_ashrrev_i32_e32 v238, 5, v237
	v_ashrrev_i32_e32 v239, 31, v238
	v_lshl_add_u64 v[240:241], s[40:41], 0, v[238:239]
	v_lshlrev_b64 v[238:239], 12, v[240:241]
	v_lshl_add_u64 v[242:243], v[0:1], 0, v[238:239]
	global_load_dwordx4 v[176:179], v[242:243], off
	v_add_u32_e32 v238, s24, v91
	v_mov_b64_e32 v[236:237], s[44:45]
	v_add_u32_e32 v239, 0x400, v238
	v_ashrrev_i32_e32 v240, 5, v239
	v_ashrrev_i32_e32 v241, 31, v240
	v_lshl_add_u64 v[242:243], s[40:41], 0, v[240:241]
	v_mad_u64_u32 v[240:241], s[26:27], v242, s22, v[236:237]
	v_mad_i32_i24 v241, v243, s22, v241
	v_lshl_add_u64 v[240:241], v[240:241], 0, v[4:5]
	v_add_co_u32_e32 v240, vcc, s21, v240
	s_nop 1
	v_addc_co_u32_e32 v241, vcc, 0, v241, vcc
	global_load_dwordx2 v[174:175], v[240:241], off
	v_add_u32_e32 v236, s24, v91
	v_add_u32_e32 v237, 0x400, v236
	v_ashrrev_i32_e32 v238, 5, v237
	v_ashrrev_i32_e32 v239, 31, v238
	v_lshl_add_u64 v[240:241], s[40:41], 0, v[238:239]
	v_lshlrev_b64 v[238:239], 12, v[240:241]
	v_lshl_add_u64 v[242:243], v[0:1], 0, v[238:239]
	global_load_dwordx4 v[180:183], v[242:243], off
	v_add_u32_e32 v238, s24, v91
	v_mov_b64_e32 v[236:237], s[44:45]
	v_add_u32_e32 v239, 0x500, v238
	v_ashrrev_i32_e32 v240, 5, v239
	v_ashrrev_i32_e32 v241, 31, v240
	v_lshl_add_u64 v[242:243], s[40:41], 0, v[240:241]
	v_mad_u64_u32 v[240:241], s[26:27], v242, s22, v[236:237]
	v_mad_i32_i24 v241, v243, s22, v241
	v_lshl_add_u64 v[240:241], v[240:241], 0, v[4:5]
	v_add_co_u32_e32 v240, vcc, s21, v240
	s_nop 1
	v_addc_co_u32_e32 v241, vcc, 0, v241, vcc
	global_load_dwordx2 v[208:209], v[240:241], off
	v_add_u32_e32 v236, s24, v91
	v_add_u32_e32 v237, 0x500, v236
	v_ashrrev_i32_e32 v238, 5, v237
	v_ashrrev_i32_e32 v239, 31, v238
	v_lshl_add_u64 v[240:241], s[40:41], 0, v[238:239]
	v_lshlrev_b64 v[238:239], 12, v[240:241]
	v_lshl_add_u64 v[242:243], v[0:1], 0, v[238:239]
	global_load_dwordx4 v[212:215], v[242:243], off
	v_add_u32_e32 v238, s24, v91
	v_mov_b64_e32 v[236:237], s[44:45]
	v_add_u32_e32 v239, 0x600, v238
	v_ashrrev_i32_e32 v240, 5, v239
	v_ashrrev_i32_e32 v241, 31, v240
	v_lshl_add_u64 v[242:243], s[40:41], 0, v[240:241]
	v_mad_u64_u32 v[240:241], s[26:27], v242, s22, v[236:237]
	v_mad_i32_i24 v241, v243, s22, v241
	v_lshl_add_u64 v[240:241], v[240:241], 0, v[4:5]
	v_add_co_u32_e32 v240, vcc, s21, v240
	s_nop 1
	v_addc_co_u32_e32 v241, vcc, 0, v241, vcc
	global_load_dwordx2 v[210:211], v[240:241], off
	v_add_u32_e32 v236, s24, v91
	v_add_u32_e32 v237, 0x600, v236
	v_ashrrev_i32_e32 v238, 5, v237
	v_ashrrev_i32_e32 v239, 31, v238
	v_lshl_add_u64 v[240:241], s[40:41], 0, v[238:239]
	v_lshlrev_b64 v[238:239], 12, v[240:241]
	v_lshl_add_u64 v[242:243], v[0:1], 0, v[238:239]
	global_load_dwordx4 v[216:219], v[242:243], off
	v_add_u32_e32 v238, s24, v91
	v_mov_b64_e32 v[236:237], s[44:45]
	v_add_u32_e32 v238, 0x700, v238
	v_ashrrev_i32_e32 v238, 5, v238
	v_ashrrev_i32_e32 v239, 31, v238
	v_lshl_add_u64 v[240:241], s[40:41], 0, v[238:239]
	v_mad_u64_u32 v[236:237], s[26:27], v240, s22, v[236:237]
	v_mad_i32_i24 v237, v241, s22, v237
	v_lshl_add_u64 v[236:237], v[236:237], 0, v[4:5]
	v_add_co_u32_e32 v236, vcc, s21, v236
	s_nop 1
	v_addc_co_u32_e32 v237, vcc, 0, v237, vcc
	global_load_dwordx2 v[220:221], v[236:237], off
	v_add_u32_e32 v238, s24, v91
	v_add_u32_e32 v238, 0x700, v238
	v_ashrrev_i32_e32 v238, 5, v238
	v_ashrrev_i32_e32 v239, 31, v238
	v_lshl_add_u64 v[240:241], s[40:41], 0, v[238:239]
	v_lshlrev_b64 v[236:237], 12, v[240:241]
	v_lshl_add_u64 v[242:243], v[0:1], 0, v[236:237]
	global_load_dwordx4 v[224:227], v[242:243], off
	s_waitcnt vmcnt(0)
; DEVI float sigmoidf_(float x) { return 1.f / (1.f + __expf(-x)); }
; template <int BR, int IN, int OUT>
; DEVI void p6_branch(const Params& P, int pm, int pn, float* macc, char* smem, int tid) {
;     ...
; #pragma unroll 8
;   for (int q = 0; q < 16; ++q) {
;     const int id = tid + 256 * q, row = id >> 5, c4 = id & 31;
;     const long grow = (long)pm * 128 + row;
;     const int gcol = pn * 128 + c4 * 4;
;     float4 a = *reinterpret_cast<const float4*>(T + row * 128 + c4 * 4);
;     float g[4];
;     load4bf(Z + grow * NCOL + (9 + BR) * 1024 + gcol, g);
;     float v[4] = {sigmoidf_(g[0]) * a.x, sigmoidf_(g[1]) * a.y, sigmoidf_(g[2]) * a.z, sigmoidf_(g[3]) * a.w};
;     if (IN == 1) {
;       float mo[4]; load4bf(M + grow * 1024 + gcol, mo);
;       v[0] += mo[0]; v[1] += mo[1]; v[2] += mo[2]; v[3] += mo[3];
;     }
;     if (IN == 2) {
;       float4 mo = *reinterpret_cast<const float4*>(macc + grow * 1024 + gcol);
;       v[0] += mo.x; v[1] += mo.y; v[2] += mo.z; v[3] += mo.w;
;     }
;     if (OUT == 1) *reinterpret_cast<float4*>(macc + grow * 1024 + gcol) = make_float4(v[0], v[1], v[2], v[3]);
;     else store4bf(M + grow * 1024 + gcol, v);
	v_add_u32_e32 v8, s24, v91
	v_ashrrev_i32_e32 v6, 5, v8
	v_ashrrev_i32_e32 v7, 31, v6
	v_lshl_add_u64 v[10:11], s[40:41], 0, v[6:7]
	v_lshl_or_b32 v9, v6, 9, v152
	v_mov_b64_e32 v[6:7], s[44:45]
	v_mad_u64_u32 v[12:13], s[26:27], v10, s22, v[6:7]
	v_mad_i32_i24 v13, v11, s22, v13
	v_lshl_add_u64 v[12:13], v[12:13], 0, v[4:5]
	v_add_co_u32_e32 v12, vcc, 0x5000, v12
	s_addk_i32 s24, 0x800
	s_nop 0
	v_addc_co_u32_e32 v13, vcc, 0, v13, vcc
	v_mov_b32_e32 v12, v154
	v_mov_b32_e32 v13, v155
	s_cmpk_lg_i32 s24, 0x1000
	v_lshlrev_b32_e32 v14, 16, v12
	v_and_b32_e32 v12, 0xffff0000, v12
	v_lshlrev_b32_e32 v15, 16, v13
	v_mul_f32_e32 v12, 0xbfb8aa3b, v12
	v_mul_f32_e32 v14, 0xbfb8aa3b, v14
	v_exp_f32_e32 v16, v12
	v_mul_f32_e32 v12, 0xbfb8aa3b, v15
	v_exp_f32_e32 v14, v14
	v_exp_f32_e32 v15, v12
	v_and_b32_e32 v13, 0xffff0000, v13
	v_mul_f32_e32 v12, 0xbfb8aa3b, v13
	v_exp_f32_e32 v17, v12
	v_lshlrev_b64 v[12:13], 12, v[10:11]
	v_lshlrev_b64 v[10:11], 11, v[10:11]
	v_pk_add_f32 v[14:15], v[14:15], 1.0 op_sel_hi:[1,0]
	v_lshl_add_u64 v[18:19], v[0:1], 0, v[12:13]
	v_lshl_add_u64 v[20:21], v[2:3], 0, v[10:11]
	ds_read_b128 v[10:13], v9
	v_div_scale_f32 v9, s[26:27], v15, v15, 1.0
	v_rcp_f32_e32 v22, v9
	s_nop 0
	v_fma_f32 v23, -v9, v22, 1.0
	v_fmac_f32_e32 v22, v23, v22
	v_div_scale_f32 v23, vcc, 1.0, v15, 1.0
	v_mul_f32_e32 v24, v23, v22
	v_fma_f32 v25, -v9, v24, v23
	v_fmac_f32_e32 v24, v25, v22
	v_fma_f32 v9, -v9, v24, v23
	v_div_fmas_f32 v9, v9, v22, v24
	v_div_fixup_f32 v23, v9, v15, 1.0
	v_div_scale_f32 v9, s[26:27], v14, v14, 1.0
	v_rcp_f32_e32 v15, v9
	s_nop 0
	v_fma_f32 v22, -v9, v15, 1.0
	v_fmac_f32_e32 v15, v22, v15
	v_div_scale_f32 v22, vcc, 1.0, v14, 1.0
	v_mul_f32_e32 v24, v22, v15
	v_fma_f32 v25, -v9, v24, v22
	v_fmac_f32_e32 v24, v25, v15
	v_fma_f32 v9, -v9, v24, v22
	v_div_fmas_f32 v9, v9, v15, v24
	v_div_fixup_f32 v22, v9, v14, 1.0
	v_pk_add_f32 v[14:15], v[16:17], 1.0 op_sel_hi:[1,0]
	s_waitcnt lgkmcnt(0)
	v_mov_b32_e32 v24, v10
	v_div_scale_f32 v9, s[26:27], v15, v15, 1.0
	v_rcp_f32_e32 v10, v9
	v_mov_b32_e32 v25, v12
	v_fma_f32 v12, -v9, v10, 1.0
	v_fmac_f32_e32 v10, v12, v10
	v_div_scale_f32 v12, vcc, 1.0, v15, 1.0
	v_mul_f32_e32 v16, v12, v10
	v_fma_f32 v17, -v9, v16, v12
	v_fmac_f32_e32 v16, v17, v10
	v_fma_f32 v9, -v9, v16, v12
	v_div_fmas_f32 v9, v9, v10, v16
	v_div_fixup_f32 v27, v9, v15, 1.0
	v_div_scale_f32 v9, s[26:27], v14, v14, 1.0
	v_rcp_f32_e32 v10, v9
	s_nop 0
	v_fma_f32 v12, -v9, v10, 1.0
	v_fmac_f32_e32 v10, v12, v10
	v_div_scale_f32 v12, vcc, 1.0, v14, 1.0
	v_mul_f32_e32 v15, v12, v10
	v_fma_f32 v16, -v9, v15, v12
	v_fmac_f32_e32 v15, v16, v10
	v_fma_f32 v9, -v9, v15, v12
	v_div_fmas_f32 v9, v9, v10, v15
	v_div_fixup_f32 v26, v9, v14, 1.0
	v_mov_b32_e32 v14, v156
	v_mov_b32_e32 v15, v157
	v_mov_b32_e32 v16, v158
	v_mov_b32_e32 v17, v159
	v_mov_b32_e32 v12, v11
	v_mov_b32_e32 v10, v14
	v_mov_b32_e32 v11, v16
	v_pk_fma_f32 v[10:11], v[24:25], v[22:23], v[10:11]
	v_mov_b32_e32 v16, v15
	v_pk_fma_f32 v[12:13], v[12:13], v[26:27], v[16:17]
	v_and_b32_sdwa v9, v11, v95 dst_sel:DWORD dst_unused:UNUSED_PAD src0_sel:WORD_1 src1_sel:DWORD
	v_and_b32_sdwa v14, v10, v95 dst_sel:DWORD dst_unused:UNUSED_PAD src0_sel:WORD_1 src1_sel:DWORD
	v_add3_u32 v10, v10, v14, s39
	v_add3_u32 v9, v11, v9, s39
	v_and_b32_sdwa v11, v13, v95 dst_sel:DWORD dst_unused:UNUSED_PAD src0_sel:WORD_1 src1_sel:DWORD
	v_and_b32_sdwa v14, v12, v95 dst_sel:DWORD dst_unused:UNUSED_PAD src0_sel:WORD_1 src1_sel:DWORD
	v_add3_u32 v11, v13, v11, s39
	v_add3_u32 v12, v12, v14, s39
	v_and_b32_e32 v11, 0xffff0000, v11
	v_and_b32_e32 v12, 0xffff0000, v12
	v_or_b32_sdwa v11, v11, v9 dst_sel:DWORD dst_unused:UNUSED_PAD src0_sel:DWORD src1_sel:WORD_1
	v_or_b32_sdwa v10, v12, v10 dst_sel:DWORD dst_unused:UNUSED_PAD src0_sel:DWORD src1_sel:WORD_1
	v_add_u32_e32 v9, 0x100, v8
	global_store_dwordx2 v[20:21], v[10:11], off
	v_ashrrev_i32_e32 v10, 5, v9
	v_ashrrev_i32_e32 v11, 31, v10
	v_lshl_add_u64 v[12:13], s[40:41], 0, v[10:11]
	v_lshl_or_b32 v9, v10, 9, v152
	v_mad_u64_u32 v[10:11], s[26:27], v12, s22, v[6:7]
	v_mad_i32_i24 v11, v13, s22, v11
	v_lshl_add_u64 v[10:11], v[10:11], 0, v[4:5]
	v_add_co_u32_e32 v10, vcc, s21, v10
	s_nop 1
	v_addc_co_u32_e32 v11, vcc, 0, v11, vcc
	v_mov_b32_e32 v10, v160
	v_mov_b32_e32 v11, v161
	v_lshlrev_b32_e32 v14, 16, v10
	v_and_b32_e32 v10, 0xffff0000, v10
	v_lshlrev_b32_e32 v15, 16, v11
	v_mul_f32_e32 v10, 0xbfb8aa3b, v10
	v_mul_f32_e32 v14, 0xbfb8aa3b, v14
	v_exp_f32_e32 v16, v10
	v_mul_f32_e32 v10, 0xbfb8aa3b, v15
	v_exp_f32_e32 v14, v14
	v_exp_f32_e32 v15, v10
	v_and_b32_e32 v11, 0xffff0000, v11
	v_mul_f32_e32 v10, 0xbfb8aa3b, v11
	v_exp_f32_e32 v17, v10
	v_lshlrev_b64 v[10:11], 12, v[12:13]
	v_lshl_add_u64 v[18:19], v[0:1], 0, v[10:11]
	v_lshlrev_b64 v[10:11], 11, v[12:13]
	v_pk_add_f32 v[14:15], v[14:15], 1.0 op_sel_hi:[1,0]
	v_lshl_add_u64 v[20:21], v[2:3], 0, v[10:11]
	ds_read_b128 v[10:13], v9
	v_div_scale_f32 v9, s[26:27], v15, v15, 1.0
	v_rcp_f32_e32 v22, v9
	s_nop 0
	v_fma_f32 v23, -v9, v22, 1.0
	v_fmac_f32_e32 v22, v23, v22
	v_div_scale_f32 v23, vcc, 1.0, v15, 1.0
	v_mul_f32_e32 v24, v23, v22
	v_fma_f32 v25, -v9, v24, v23
	v_fmac_f32_e32 v24, v25, v22
	v_fma_f32 v9, -v9, v24, v23
	v_div_fmas_f32 v9, v9, v22, v24
	v_div_fixup_f32 v23, v9, v15, 1.0
	v_div_scale_f32 v9, s[26:27], v14, v14, 1.0
	v_rcp_f32_e32 v15, v9
	s_nop 0
	v_fma_f32 v22, -v9, v15, 1.0
	v_fmac_f32_e32 v15, v22, v15
	v_div_scale_f32 v22, vcc, 1.0, v14, 1.0
	v_mul_f32_e32 v24, v22, v15
	v_fma_f32 v25, -v9, v24, v22
	v_fmac_f32_e32 v24, v25, v15
	v_fma_f32 v9, -v9, v24, v22
	v_div_fmas_f32 v9, v9, v15, v24
	v_div_fixup_f32 v22, v9, v14, 1.0
	v_pk_add_f32 v[14:15], v[16:17], 1.0 op_sel_hi:[1,0]
	s_waitcnt lgkmcnt(0)
; DEVI float sigmoidf_(float x) { return 1.f / (1.f + __expf(-x)); }
; template <int BR, int IN, int OUT>
; DEVI void p6_branch(const Params& P, int pm, int pn, float* macc, char* smem, int tid) {
;     ...
; #pragma unroll 8
;   for (int q = 0; q < 16; ++q) {
;     const int id = tid + 256 * q, row = id >> 5, c4 = id & 31;
;     const long grow = (long)pm * 128 + row;
;     const int gcol = pn * 128 + c4 * 4;
;     float4 a = *reinterpret_cast<const float4*>(T + row * 128 + c4 * 4);
;     float g[4];
;     load4bf(Z + grow * NCOL + (9 + BR) * 1024 + gcol, g);
;     float v[4] = {sigmoidf_(g[0]) * a.x, sigmoidf_(g[1]) * a.y, sigmoidf_(g[2]) * a.z, sigmoidf_(g[3]) * a.w};
;     if (IN == 1) {
;       float mo[4]; load4bf(M + grow * 1024 + gcol, mo);
;       v[0] += mo[0]; v[1] += mo[1]; v[2] += mo[2]; v[3] += mo[3];
;     }
;     if (IN == 2) {
;       float4 mo = *reinterpret_cast<const float4*>(macc + grow * 1024 + gcol);
;       v[0] += mo.x; v[1] += mo.y; v[2] += mo.z; v[3] += mo.w;
;     }
;     if (OUT == 1) *reinterpret_cast<float4*>(macc + grow * 1024 + gcol) = make_float4(v[0], v[1], v[2], v[3]);
;     else store4bf(M + grow * 1024 + gcol, v);
	v_mov_b32_e32 v24, v10
	v_div_scale_f32 v9, s[26:27], v15, v15, 1.0
	v_rcp_f32_e32 v10, v9
	v_mov_b32_e32 v25, v12
	v_fma_f32 v12, -v9, v10, 1.0
	v_fmac_f32_e32 v10, v12, v10
	v_div_scale_f32 v12, vcc, 1.0, v15, 1.0
	v_mul_f32_e32 v16, v12, v10
	v_fma_f32 v17, -v9, v16, v12
	v_fmac_f32_e32 v16, v17, v10
	v_fma_f32 v9, -v9, v16, v12
	v_div_fmas_f32 v9, v9, v10, v16
	v_div_fixup_f32 v27, v9, v15, 1.0
	v_div_scale_f32 v9, s[26:27], v14, v14, 1.0
	v_rcp_f32_e32 v10, v9
	s_nop 0
	v_fma_f32 v12, -v9, v10, 1.0
	v_fmac_f32_e32 v10, v12, v10
	v_div_scale_f32 v12, vcc, 1.0, v14, 1.0
	v_mul_f32_e32 v15, v12, v10
	v_fma_f32 v16, -v9, v15, v12
	v_fmac_f32_e32 v15, v16, v10
	v_fma_f32 v9, -v9, v15, v12
	v_div_fmas_f32 v9, v9, v10, v15
	v_div_fixup_f32 v26, v9, v14, 1.0
	v_mov_b32_e32 v14, v164
	v_mov_b32_e32 v15, v165
	v_mov_b32_e32 v16, v166
	v_mov_b32_e32 v17, v167
	v_mov_b32_e32 v12, v11
	v_mov_b32_e32 v10, v14
	v_mov_b32_e32 v11, v16
	v_pk_fma_f32 v[10:11], v[24:25], v[22:23], v[10:11]
	v_mov_b32_e32 v16, v15
	v_pk_fma_f32 v[12:13], v[12:13], v[26:27], v[16:17]
	v_and_b32_sdwa v9, v11, v95 dst_sel:DWORD dst_unused:UNUSED_PAD src0_sel:WORD_1 src1_sel:DWORD
	v_and_b32_sdwa v14, v10, v95 dst_sel:DWORD dst_unused:UNUSED_PAD src0_sel:WORD_1 src1_sel:DWORD
	v_add3_u32 v10, v10, v14, s39
	v_add3_u32 v9, v11, v9, s39
	v_and_b32_sdwa v11, v13, v95 dst_sel:DWORD dst_unused:UNUSED_PAD src0_sel:WORD_1 src1_sel:DWORD
	v_and_b32_sdwa v14, v12, v95 dst_sel:DWORD dst_unused:UNUSED_PAD src0_sel:WORD_1 src1_sel:DWORD
	v_add3_u32 v11, v13, v11, s39
	v_add3_u32 v12, v12, v14, s39
	v_and_b32_e32 v11, 0xffff0000, v11
	v_and_b32_e32 v12, 0xffff0000, v12
	v_or_b32_sdwa v11, v11, v9 dst_sel:DWORD dst_unused:UNUSED_PAD src0_sel:DWORD src1_sel:WORD_1
	v_or_b32_sdwa v10, v12, v10 dst_sel:DWORD dst_unused:UNUSED_PAD src0_sel:DWORD src1_sel:WORD_1
	v_add_u32_e32 v9, 0x200, v8
	global_store_dwordx2 v[20:21], v[10:11], off
	v_ashrrev_i32_e32 v10, 5, v9
	v_ashrrev_i32_e32 v11, 31, v10
	v_lshl_add_u64 v[12:13], s[40:41], 0, v[10:11]
	v_lshl_or_b32 v9, v10, 9, v152
	v_mad_u64_u32 v[10:11], s[26:27], v12, s22, v[6:7]
	v_mad_i32_i24 v11, v13, s22, v11
	v_lshl_add_u64 v[10:11], v[10:11], 0, v[4:5]
	v_add_co_u32_e32 v10, vcc, s21, v10
	s_nop 1
	v_addc_co_u32_e32 v11, vcc, 0, v11, vcc
	v_mov_b32_e32 v10, v162
	v_mov_b32_e32 v11, v163
	v_lshlrev_b32_e32 v14, 16, v10
	v_and_b32_e32 v10, 0xffff0000, v10
	v_lshlrev_b32_e32 v15, 16, v11
	v_mul_f32_e32 v10, 0xbfb8aa3b, v10
	v_mul_f32_e32 v14, 0xbfb8aa3b, v14
	v_exp_f32_e32 v16, v10
	v_mul_f32_e32 v10, 0xbfb8aa3b, v15
	v_exp_f32_e32 v14, v14
	v_exp_f32_e32 v15, v10
	v_and_b32_e32 v11, 0xffff0000, v11
	v_mul_f32_e32 v10, 0xbfb8aa3b, v11
	v_exp_f32_e32 v17, v10
	v_lshlrev_b64 v[10:11], 12, v[12:13]
	v_lshl_add_u64 v[18:19], v[0:1], 0, v[10:11]
	v_lshlrev_b64 v[10:11], 11, v[12:13]
	v_pk_add_f32 v[14:15], v[14:15], 1.0 op_sel_hi:[1,0]
	v_lshl_add_u64 v[20:21], v[2:3], 0, v[10:11]
	ds_read_b128 v[10:13], v9
	v_div_scale_f32 v9, s[26:27], v15, v15, 1.0
	v_rcp_f32_e32 v22, v9
	s_nop 0
	v_fma_f32 v23, -v9, v22, 1.0
	v_fmac_f32_e32 v22, v23, v22
	v_div_scale_f32 v23, vcc, 1.0, v15, 1.0
	v_mul_f32_e32 v24, v23, v22
	v_fma_f32 v25, -v9, v24, v23
	v_fmac_f32_e32 v24, v25, v22
	v_fma_f32 v9, -v9, v24, v23
	v_div_fmas_f32 v9, v9, v22, v24
	v_div_fixup_f32 v23, v9, v15, 1.0
	v_div_scale_f32 v9, s[26:27], v14, v14, 1.0
	v_rcp_f32_e32 v15, v9
	s_nop 0
	v_fma_f32 v22, -v9, v15, 1.0
	v_fmac_f32_e32 v15, v22, v15
	v_div_scale_f32 v22, vcc, 1.0, v14, 1.0
	v_mul_f32_e32 v24, v22, v15
	v_fma_f32 v25, -v9, v24, v22
	v_fmac_f32_e32 v24, v25, v15
	v_fma_f32 v9, -v9, v24, v22
	v_div_fmas_f32 v9, v9, v15, v24
	v_div_fixup_f32 v22, v9, v14, 1.0
	v_pk_add_f32 v[14:15], v[16:17], 1.0 op_sel_hi:[1,0]
	s_waitcnt lgkmcnt(0)
	v_mov_b32_e32 v24, v10
	v_div_scale_f32 v9, s[26:27], v15, v15, 1.0
	v_rcp_f32_e32 v10, v9
	v_mov_b32_e32 v25, v12
	v_fma_f32 v12, -v9, v10, 1.0
	v_fmac_f32_e32 v10, v12, v10
	v_div_scale_f32 v12, vcc, 1.0, v15, 1.0
	v_mul_f32_e32 v16, v12, v10
	v_fma_f32 v17, -v9, v16, v12
	v_fmac_f32_e32 v16, v17, v10
	v_fma_f32 v9, -v9, v16, v12
	v_div_fmas_f32 v9, v9, v10, v16
	v_div_fixup_f32 v27, v9, v15, 1.0
	v_div_scale_f32 v9, s[26:27], v14, v14, 1.0
	v_rcp_f32_e32 v10, v9
	s_nop 0
	v_fma_f32 v12, -v9, v10, 1.0
	v_fmac_f32_e32 v10, v12, v10
	v_div_scale_f32 v12, vcc, 1.0, v14, 1.0
	v_mul_f32_e32 v15, v12, v10
	v_fma_f32 v16, -v9, v15, v12
	v_fmac_f32_e32 v15, v16, v10
	v_fma_f32 v9, -v9, v15, v12
	v_div_fmas_f32 v9, v9, v10, v15
	v_div_fixup_f32 v26, v9, v14, 1.0
	v_mov_b32_e32 v14, v168
	v_mov_b32_e32 v15, v169
	v_mov_b32_e32 v16, v170
	v_mov_b32_e32 v17, v171
	v_mov_b32_e32 v12, v11
	v_mov_b32_e32 v10, v14
	v_mov_b32_e32 v11, v16
	v_pk_fma_f32 v[10:11], v[24:25], v[22:23], v[10:11]
	v_mov_b32_e32 v16, v15
	v_pk_fma_f32 v[12:13], v[12:13], v[26:27], v[16:17]
	v_and_b32_sdwa v9, v11, v95 dst_sel:DWORD dst_unused:UNUSED_PAD src0_sel:WORD_1 src1_sel:DWORD
	v_and_b32_sdwa v14, v10, v95 dst_sel:DWORD dst_unused:UNUSED_PAD src0_sel:WORD_1 src1_sel:DWORD
	v_add3_u32 v10, v10, v14, s39
	v_add3_u32 v9, v11, v9, s39
	v_and_b32_sdwa v11, v13, v95 dst_sel:DWORD dst_unused:UNUSED_PAD src0_sel:WORD_1 src1_sel:DWORD
	v_and_b32_sdwa v14, v12, v95 dst_sel:DWORD dst_unused:UNUSED_PAD src0_sel:WORD_1 src1_sel:DWORD
	v_add3_u32 v11, v13, v11, s39
	v_add3_u32 v12, v12, v14, s39
	v_and_b32_e32 v11, 0xffff0000, v11
	v_and_b32_e32 v12, 0xffff0000, v12
	v_or_b32_sdwa v11, v11, v9 dst_sel:DWORD dst_unused:UNUSED_PAD src0_sel:DWORD src1_sel:WORD_1
	v_or_b32_sdwa v10, v12, v10 dst_sel:DWORD dst_unused:UNUSED_PAD src0_sel:DWORD src1_sel:WORD_1
	v_add_u32_e32 v9, 0x300, v8
; DEVI float sigmoidf_(float x) { return 1.f / (1.f + __expf(-x)); }
; template <int BR, int IN, int OUT>
; DEVI void p6_branch(const Params& P, int pm, int pn, float* macc, char* smem, int tid) {
;     ...
; #pragma unroll 8
;   for (int q = 0; q < 16; ++q) {
;     const int id = tid + 256 * q, row = id >> 5, c4 = id & 31;
;     const long grow = (long)pm * 128 + row;
;     const int gcol = pn * 128 + c4 * 4;
;     float4 a = *reinterpret_cast<const float4*>(T + row * 128 + c4 * 4);
;     float g[4];
;     load4bf(Z + grow * NCOL + (9 + BR) * 1024 + gcol, g);
;     float v[4] = {sigmoidf_(g[0]) * a.x, sigmoidf_(g[1]) * a.y, sigmoidf_(g[2]) * a.z, sigmoidf_(g[3]) * a.w};
;     if (IN == 1) {
;       float mo[4]; load4bf(M + grow * 1024 + gcol, mo);
;       v[0] += mo[0]; v[1] += mo[1]; v[2] += mo[2]; v[3] += mo[3];
;     }
;     if (IN == 2) {
;       float4 mo = *reinterpret_cast<const float4*>(macc + grow * 1024 + gcol);
;       v[0] += mo.x; v[1] += mo.y; v[2] += mo.z; v[3] += mo.w;
;     }
;     if (OUT == 1) *reinterpret_cast<float4*>(macc + grow * 1024 + gcol) = make_float4(v[0], v[1], v[2], v[3]);
;     else store4bf(M + grow * 1024 + gcol, v);
	global_store_dwordx2 v[20:21], v[10:11], off
	v_ashrrev_i32_e32 v10, 5, v9
	v_ashrrev_i32_e32 v11, 31, v10
	v_lshl_add_u64 v[12:13], s[40:41], 0, v[10:11]
	v_lshl_or_b32 v9, v10, 9, v152
	v_mad_u64_u32 v[10:11], s[26:27], v12, s22, v[6:7]
	v_mad_i32_i24 v11, v13, s22, v11
	v_lshl_add_u64 v[10:11], v[10:11], 0, v[4:5]
	v_add_co_u32_e32 v10, vcc, s21, v10
	s_nop 1
	v_addc_co_u32_e32 v11, vcc, 0, v11, vcc
	v_mov_b32_e32 v10, v172
	v_mov_b32_e32 v11, v173
	v_lshlrev_b32_e32 v14, 16, v10
	v_and_b32_e32 v10, 0xffff0000, v10
	v_lshlrev_b32_e32 v15, 16, v11
	v_mul_f32_e32 v10, 0xbfb8aa3b, v10
	v_mul_f32_e32 v14, 0xbfb8aa3b, v14
	v_exp_f32_e32 v16, v10
	v_mul_f32_e32 v10, 0xbfb8aa3b, v15
	v_exp_f32_e32 v14, v14
	v_exp_f32_e32 v15, v10
	v_and_b32_e32 v11, 0xffff0000, v11
	v_mul_f32_e32 v10, 0xbfb8aa3b, v11
	v_exp_f32_e32 v17, v10
	v_lshlrev_b64 v[10:11], 12, v[12:13]
	v_lshl_add_u64 v[18:19], v[0:1], 0, v[10:11]
	v_lshlrev_b64 v[10:11], 11, v[12:13]
	v_pk_add_f32 v[14:15], v[14:15], 1.0 op_sel_hi:[1,0]
	v_lshl_add_u64 v[20:21], v[2:3], 0, v[10:11]
	ds_read_b128 v[10:13], v9
	v_div_scale_f32 v9, s[26:27], v15, v15, 1.0
	v_rcp_f32_e32 v22, v9
	s_nop 0
	v_fma_f32 v23, -v9, v22, 1.0
	v_fmac_f32_e32 v22, v23, v22
	v_div_scale_f32 v23, vcc, 1.0, v15, 1.0
	v_mul_f32_e32 v24, v23, v22
	v_fma_f32 v25, -v9, v24, v23
	v_fmac_f32_e32 v24, v25, v22
	v_fma_f32 v9, -v9, v24, v23
	v_div_fmas_f32 v9, v9, v22, v24
	v_div_fixup_f32 v23, v9, v15, 1.0
	v_div_scale_f32 v9, s[26:27], v14, v14, 1.0
	v_rcp_f32_e32 v15, v9
	s_nop 0
	v_fma_f32 v22, -v9, v15, 1.0
	v_fmac_f32_e32 v15, v22, v15
	v_div_scale_f32 v22, vcc, 1.0, v14, 1.0
	v_mul_f32_e32 v24, v22, v15
	v_fma_f32 v25, -v9, v24, v22
	v_fmac_f32_e32 v24, v25, v15
	v_fma_f32 v9, -v9, v24, v22
	v_div_fmas_f32 v9, v9, v15, v24
	v_div_fixup_f32 v22, v9, v14, 1.0
	v_pk_add_f32 v[14:15], v[16:17], 1.0 op_sel_hi:[1,0]
	s_waitcnt lgkmcnt(0)
	v_mov_b32_e32 v24, v10
	v_div_scale_f32 v9, s[26:27], v15, v15, 1.0
	v_rcp_f32_e32 v10, v9
	v_mov_b32_e32 v25, v12
	v_fma_f32 v12, -v9, v10, 1.0
	v_fmac_f32_e32 v10, v12, v10
	v_div_scale_f32 v12, vcc, 1.0, v15, 1.0
	v_mul_f32_e32 v16, v12, v10
	v_fma_f32 v17, -v9, v16, v12
	v_fmac_f32_e32 v16, v17, v10
	v_fma_f32 v9, -v9, v16, v12
	v_div_fmas_f32 v9, v9, v10, v16
	v_div_fixup_f32 v27, v9, v15, 1.0
	v_div_scale_f32 v9, s[26:27], v14, v14, 1.0
	v_rcp_f32_e32 v10, v9
	s_nop 0
	v_fma_f32 v12, -v9, v10, 1.0
	v_fmac_f32_e32 v10, v12, v10
	v_div_scale_f32 v12, vcc, 1.0, v14, 1.0
	v_mul_f32_e32 v15, v12, v10
	v_fma_f32 v16, -v9, v15, v12
	v_fmac_f32_e32 v15, v16, v10
	v_fma_f32 v9, -v9, v15, v12
	v_div_fmas_f32 v9, v9, v10, v15
	v_div_fixup_f32 v26, v9, v14, 1.0
	v_mov_b32_e32 v14, v176
	v_mov_b32_e32 v15, v177
	v_mov_b32_e32 v16, v178
	v_mov_b32_e32 v17, v179
	v_mov_b32_e32 v12, v11
	v_mov_b32_e32 v10, v14
	v_mov_b32_e32 v11, v16
	v_pk_fma_f32 v[10:11], v[24:25], v[22:23], v[10:11]
	v_mov_b32_e32 v16, v15
	v_pk_fma_f32 v[12:13], v[12:13], v[26:27], v[16:17]
	v_and_b32_sdwa v9, v11, v95 dst_sel:DWORD dst_unused:UNUSED_PAD src0_sel:WORD_1 src1_sel:DWORD
	v_and_b32_sdwa v14, v10, v95 dst_sel:DWORD dst_unused:UNUSED_PAD src0_sel:WORD_1 src1_sel:DWORD
	v_add3_u32 v10, v10, v14, s39
	v_add3_u32 v9, v11, v9, s39
	v_and_b32_sdwa v11, v13, v95 dst_sel:DWORD dst_unused:UNUSED_PAD src0_sel:WORD_1 src1_sel:DWORD
	v_and_b32_sdwa v14, v12, v95 dst_sel:DWORD dst_unused:UNUSED_PAD src0_sel:WORD_1 src1_sel:DWORD
	v_add3_u32 v11, v13, v11, s39
	v_add3_u32 v12, v12, v14, s39
	v_and_b32_e32 v11, 0xffff0000, v11
	v_and_b32_e32 v12, 0xffff0000, v12
	v_or_b32_sdwa v11, v11, v9 dst_sel:DWORD dst_unused:UNUSED_PAD src0_sel:DWORD src1_sel:WORD_1
	v_or_b32_sdwa v10, v12, v10 dst_sel:DWORD dst_unused:UNUSED_PAD src0_sel:DWORD src1_sel:WORD_1
	v_add_u32_e32 v9, 0x400, v8
	global_store_dwordx2 v[20:21], v[10:11], off
	v_ashrrev_i32_e32 v10, 5, v9
	v_ashrrev_i32_e32 v11, 31, v10
	v_lshl_add_u64 v[12:13], s[40:41], 0, v[10:11]
	v_lshl_or_b32 v9, v10, 9, v152
	v_mad_u64_u32 v[10:11], s[26:27], v12, s22, v[6:7]
	v_mad_i32_i24 v11, v13, s22, v11
	v_lshl_add_u64 v[10:11], v[10:11], 0, v[4:5]
	v_add_co_u32_e32 v10, vcc, s21, v10
	s_nop 1
	v_addc_co_u32_e32 v11, vcc, 0, v11, vcc
	v_mov_b32_e32 v10, v174
	v_mov_b32_e32 v11, v175
	v_lshlrev_b32_e32 v14, 16, v10
	v_and_b32_e32 v10, 0xffff0000, v10
	v_lshlrev_b32_e32 v15, 16, v11
	v_mul_f32_e32 v10, 0xbfb8aa3b, v10
	v_mul_f32_e32 v14, 0xbfb8aa3b, v14
	v_exp_f32_e32 v16, v10
	v_mul_f32_e32 v10, 0xbfb8aa3b, v15
	v_exp_f32_e32 v14, v14
	v_exp_f32_e32 v15, v10
	v_and_b32_e32 v11, 0xffff0000, v11
	v_mul_f32_e32 v10, 0xbfb8aa3b, v11
	v_exp_f32_e32 v17, v10
	v_lshlrev_b64 v[10:11], 12, v[12:13]
	v_lshl_add_u64 v[18:19], v[0:1], 0, v[10:11]
	v_lshlrev_b64 v[10:11], 11, v[12:13]
	v_pk_add_f32 v[14:15], v[14:15], 1.0 op_sel_hi:[1,0]
	v_lshl_add_u64 v[20:21], v[2:3], 0, v[10:11]
	ds_read_b128 v[10:13], v9
	v_div_scale_f32 v9, s[26:27], v15, v15, 1.0
	v_rcp_f32_e32 v22, v9
	s_nop 0
	v_fma_f32 v23, -v9, v22, 1.0
	v_fmac_f32_e32 v22, v23, v22
	v_div_scale_f32 v23, vcc, 1.0, v15, 1.0
	v_mul_f32_e32 v24, v23, v22
	v_fma_f32 v25, -v9, v24, v23
	v_fmac_f32_e32 v24, v25, v22
	v_fma_f32 v9, -v9, v24, v23
	v_div_fmas_f32 v9, v9, v22, v24
	v_div_fixup_f32 v23, v9, v15, 1.0
	v_div_scale_f32 v9, s[26:27], v14, v14, 1.0
	v_rcp_f32_e32 v15, v9
	s_nop 0
	v_fma_f32 v22, -v9, v15, 1.0
	v_fmac_f32_e32 v15, v22, v15
	v_div_scale_f32 v22, vcc, 1.0, v14, 1.0
	v_mul_f32_e32 v24, v22, v15
	v_fma_f32 v25, -v9, v24, v22
	v_fmac_f32_e32 v24, v25, v15
	v_fma_f32 v9, -v9, v24, v22
	v_div_fmas_f32 v9, v9, v15, v24
	v_div_fixup_f32 v22, v9, v14, 1.0
	v_pk_add_f32 v[14:15], v[16:17], 1.0 op_sel_hi:[1,0]
	s_waitcnt lgkmcnt(0)
; DEVI float sigmoidf_(float x) { return 1.f / (1.f + __expf(-x)); }
; template <int BR, int IN, int OUT>
; DEVI void p6_branch(const Params& P, int pm, int pn, float* macc, char* smem, int tid) {
;     ...
; #pragma unroll 8
;   for (int q = 0; q < 16; ++q) {
;     const int id = tid + 256 * q, row = id >> 5, c4 = id & 31;
;     const long grow = (long)pm * 128 + row;
;     const int gcol = pn * 128 + c4 * 4;
;     float4 a = *reinterpret_cast<const float4*>(T + row * 128 + c4 * 4);
;     float g[4];
;     load4bf(Z + grow * NCOL + (9 + BR) * 1024 + gcol, g);
;     float v[4] = {sigmoidf_(g[0]) * a.x, sigmoidf_(g[1]) * a.y, sigmoidf_(g[2]) * a.z, sigmoidf_(g[3]) * a.w};
;     if (IN == 1) {
;       float mo[4]; load4bf(M + grow * 1024 + gcol, mo);
;       v[0] += mo[0]; v[1] += mo[1]; v[2] += mo[2]; v[3] += mo[3];
;     }
;     if (IN == 2) {
;       float4 mo = *reinterpret_cast<const float4*>(macc + grow * 1024 + gcol);
;       v[0] += mo.x; v[1] += mo.y; v[2] += mo.z; v[3] += mo.w;
;     }
;     if (OUT == 1) *reinterpret_cast<float4*>(macc + grow * 1024 + gcol) = make_float4(v[0], v[1], v[2], v[3]);
;     else store4bf(M + grow * 1024 + gcol, v);
	v_mov_b32_e32 v24, v10
	v_div_scale_f32 v9, s[26:27], v15, v15, 1.0
	v_rcp_f32_e32 v10, v9
	v_mov_b32_e32 v25, v12
	v_fma_f32 v12, -v9, v10, 1.0
	v_fmac_f32_e32 v10, v12, v10
	v_div_scale_f32 v12, vcc, 1.0, v15, 1.0
	v_mul_f32_e32 v16, v12, v10
	v_fma_f32 v17, -v9, v16, v12
	v_fmac_f32_e32 v16, v17, v10
	v_fma_f32 v9, -v9, v16, v12
	v_div_fmas_f32 v9, v9, v10, v16
	v_div_fixup_f32 v27, v9, v15, 1.0
	v_div_scale_f32 v9, s[26:27], v14, v14, 1.0
	v_rcp_f32_e32 v10, v9
	s_nop 0
	v_fma_f32 v12, -v9, v10, 1.0
	v_fmac_f32_e32 v10, v12, v10
	v_div_scale_f32 v12, vcc, 1.0, v14, 1.0
	v_mul_f32_e32 v15, v12, v10
	v_fma_f32 v16, -v9, v15, v12
	v_fmac_f32_e32 v15, v16, v10
	v_fma_f32 v9, -v9, v15, v12
	v_div_fmas_f32 v9, v9, v10, v15
	v_div_fixup_f32 v26, v9, v14, 1.0
	v_mov_b32_e32 v14, v180
	v_mov_b32_e32 v15, v181
	v_mov_b32_e32 v16, v182
	v_mov_b32_e32 v17, v183
	v_mov_b32_e32 v12, v11
	v_mov_b32_e32 v10, v14
	v_mov_b32_e32 v11, v16
	v_pk_fma_f32 v[10:11], v[24:25], v[22:23], v[10:11]
	v_mov_b32_e32 v16, v15
	v_pk_fma_f32 v[12:13], v[12:13], v[26:27], v[16:17]
	v_and_b32_sdwa v9, v11, v95 dst_sel:DWORD dst_unused:UNUSED_PAD src0_sel:WORD_1 src1_sel:DWORD
	v_and_b32_sdwa v14, v10, v95 dst_sel:DWORD dst_unused:UNUSED_PAD src0_sel:WORD_1 src1_sel:DWORD
	v_add3_u32 v10, v10, v14, s39
	v_add3_u32 v9, v11, v9, s39
	v_and_b32_sdwa v11, v13, v95 dst_sel:DWORD dst_unused:UNUSED_PAD src0_sel:WORD_1 src1_sel:DWORD
	v_and_b32_sdwa v14, v12, v95 dst_sel:DWORD dst_unused:UNUSED_PAD src0_sel:WORD_1 src1_sel:DWORD
	v_add3_u32 v11, v13, v11, s39
	v_add3_u32 v12, v12, v14, s39
	v_and_b32_e32 v11, 0xffff0000, v11
	v_and_b32_e32 v12, 0xffff0000, v12
	v_or_b32_sdwa v11, v11, v9 dst_sel:DWORD dst_unused:UNUSED_PAD src0_sel:DWORD src1_sel:WORD_1
	v_or_b32_sdwa v10, v12, v10 dst_sel:DWORD dst_unused:UNUSED_PAD src0_sel:DWORD src1_sel:WORD_1
	v_add_u32_e32 v9, 0x500, v8
	global_store_dwordx2 v[20:21], v[10:11], off
	v_ashrrev_i32_e32 v10, 5, v9
	v_ashrrev_i32_e32 v11, 31, v10
	v_lshl_add_u64 v[12:13], s[40:41], 0, v[10:11]
	v_lshl_or_b32 v9, v10, 9, v152
	v_mad_u64_u32 v[10:11], s[26:27], v12, s22, v[6:7]
	v_mad_i32_i24 v11, v13, s22, v11
	v_lshl_add_u64 v[10:11], v[10:11], 0, v[4:5]
	v_add_co_u32_e32 v10, vcc, s21, v10
	s_nop 1
	v_addc_co_u32_e32 v11, vcc, 0, v11, vcc
	v_mov_b32_e32 v10, v208
	v_mov_b32_e32 v11, v209
	v_lshlrev_b32_e32 v14, 16, v10
	v_and_b32_e32 v10, 0xffff0000, v10
	v_lshlrev_b32_e32 v15, 16, v11
	v_mul_f32_e32 v10, 0xbfb8aa3b, v10
	v_mul_f32_e32 v14, 0xbfb8aa3b, v14
	v_exp_f32_e32 v16, v10
	v_mul_f32_e32 v10, 0xbfb8aa3b, v15
	v_exp_f32_e32 v14, v14
	v_exp_f32_e32 v15, v10
	v_and_b32_e32 v11, 0xffff0000, v11
	v_mul_f32_e32 v10, 0xbfb8aa3b, v11
	v_exp_f32_e32 v17, v10
	v_lshlrev_b64 v[10:11], 12, v[12:13]
	v_lshl_add_u64 v[18:19], v[0:1], 0, v[10:11]
	v_lshlrev_b64 v[10:11], 11, v[12:13]
	v_pk_add_f32 v[14:15], v[14:15], 1.0 op_sel_hi:[1,0]
	v_lshl_add_u64 v[20:21], v[2:3], 0, v[10:11]
	ds_read_b128 v[10:13], v9
	v_div_scale_f32 v9, s[26:27], v15, v15, 1.0
	v_rcp_f32_e32 v22, v9
	s_nop 0
	v_fma_f32 v23, -v9, v22, 1.0
	v_fmac_f32_e32 v22, v23, v22
	v_div_scale_f32 v23, vcc, 1.0, v15, 1.0
	v_mul_f32_e32 v24, v23, v22
	v_fma_f32 v25, -v9, v24, v23
	v_fmac_f32_e32 v24, v25, v22
	v_fma_f32 v9, -v9, v24, v23
	v_div_fmas_f32 v9, v9, v22, v24
	v_div_fixup_f32 v23, v9, v15, 1.0
	v_div_scale_f32 v9, s[26:27], v14, v14, 1.0
	v_rcp_f32_e32 v15, v9
	s_nop 0
	v_fma_f32 v22, -v9, v15, 1.0
	v_fmac_f32_e32 v15, v22, v15
	v_div_scale_f32 v22, vcc, 1.0, v14, 1.0
	v_mul_f32_e32 v24, v22, v15
	v_fma_f32 v25, -v9, v24, v22
	v_fmac_f32_e32 v24, v25, v15
	v_fma_f32 v9, -v9, v24, v22
	v_div_fmas_f32 v9, v9, v15, v24
	v_div_fixup_f32 v22, v9, v14, 1.0
	v_pk_add_f32 v[14:15], v[16:17], 1.0 op_sel_hi:[1,0]
	s_waitcnt lgkmcnt(0)
	v_mov_b32_e32 v24, v10
	v_div_scale_f32 v9, s[26:27], v15, v15, 1.0
	v_rcp_f32_e32 v10, v9
	v_mov_b32_e32 v25, v12
	v_fma_f32 v12, -v9, v10, 1.0
	v_fmac_f32_e32 v10, v12, v10
	v_div_scale_f32 v12, vcc, 1.0, v15, 1.0
	v_mul_f32_e32 v16, v12, v10
	v_fma_f32 v17, -v9, v16, v12
	v_fmac_f32_e32 v16, v17, v10
	v_fma_f32 v9, -v9, v16, v12
	v_div_fmas_f32 v9, v9, v10, v16
	v_div_fixup_f32 v27, v9, v15, 1.0
	v_div_scale_f32 v9, s[26:27], v14, v14, 1.0
	v_rcp_f32_e32 v10, v9
	s_nop 0
	v_fma_f32 v12, -v9, v10, 1.0
	v_fmac_f32_e32 v10, v12, v10
	v_div_scale_f32 v12, vcc, 1.0, v14, 1.0
	v_mul_f32_e32 v15, v12, v10
	v_fma_f32 v16, -v9, v15, v12
	v_fmac_f32_e32 v15, v16, v10
	v_fma_f32 v9, -v9, v15, v12
	v_div_fmas_f32 v9, v9, v10, v15
	v_div_fixup_f32 v26, v9, v14, 1.0
	v_mov_b32_e32 v14, v212
	v_mov_b32_e32 v15, v213
	v_mov_b32_e32 v16, v214
	v_mov_b32_e32 v17, v215
	v_mov_b32_e32 v12, v11
	v_mov_b32_e32 v10, v14
	v_mov_b32_e32 v11, v16
	v_pk_fma_f32 v[10:11], v[24:25], v[22:23], v[10:11]
	v_mov_b32_e32 v16, v15
	v_pk_fma_f32 v[12:13], v[12:13], v[26:27], v[16:17]
	v_and_b32_sdwa v9, v11, v95 dst_sel:DWORD dst_unused:UNUSED_PAD src0_sel:WORD_1 src1_sel:DWORD
	v_and_b32_sdwa v14, v10, v95 dst_sel:DWORD dst_unused:UNUSED_PAD src0_sel:WORD_1 src1_sel:DWORD
	v_add3_u32 v10, v10, v14, s39
	v_add3_u32 v9, v11, v9, s39
	v_and_b32_sdwa v11, v13, v95 dst_sel:DWORD dst_unused:UNUSED_PAD src0_sel:WORD_1 src1_sel:DWORD
	v_and_b32_sdwa v14, v12, v95 dst_sel:DWORD dst_unused:UNUSED_PAD src0_sel:WORD_1 src1_sel:DWORD
	v_add3_u32 v11, v13, v11, s39
	v_add3_u32 v12, v12, v14, s39
	v_and_b32_e32 v11, 0xffff0000, v11
	v_and_b32_e32 v12, 0xffff0000, v12
	v_or_b32_sdwa v11, v11, v9 dst_sel:DWORD dst_unused:UNUSED_PAD src0_sel:DWORD src1_sel:WORD_1
	v_or_b32_sdwa v10, v12, v10 dst_sel:DWORD dst_unused:UNUSED_PAD src0_sel:DWORD src1_sel:WORD_1
	v_add_u32_e32 v9, 0x600, v8
; DEVI float sigmoidf_(float x) { return 1.f / (1.f + __expf(-x)); }
; template <int BR, int IN, int OUT>
; DEVI void p6_branch(const Params& P, int pm, int pn, float* macc, char* smem, int tid) {
;     ...
; #pragma unroll 8
;   for (int q = 0; q < 16; ++q) {
;     const int id = tid + 256 * q, row = id >> 5, c4 = id & 31;
;     const long grow = (long)pm * 128 + row;
;     const int gcol = pn * 128 + c4 * 4;
;     float4 a = *reinterpret_cast<const float4*>(T + row * 128 + c4 * 4);
;     float g[4];
;     load4bf(Z + grow * NCOL + (9 + BR) * 1024 + gcol, g);
;     float v[4] = {sigmoidf_(g[0]) * a.x, sigmoidf_(g[1]) * a.y, sigmoidf_(g[2]) * a.z, sigmoidf_(g[3]) * a.w};
;     if (IN == 1) {
;       float mo[4]; load4bf(M + grow * 1024 + gcol, mo);
;       v[0] += mo[0]; v[1] += mo[1]; v[2] += mo[2]; v[3] += mo[3];
;     }
;     if (IN == 2) {
;       float4 mo = *reinterpret_cast<const float4*>(macc + grow * 1024 + gcol);
;       v[0] += mo.x; v[1] += mo.y; v[2] += mo.z; v[3] += mo.w;
;     }
;     if (OUT == 1) *reinterpret_cast<float4*>(macc + grow * 1024 + gcol) = make_float4(v[0], v[1], v[2], v[3]);
;     else store4bf(M + grow * 1024 + gcol, v);
	global_store_dwordx2 v[20:21], v[10:11], off
	v_ashrrev_i32_e32 v10, 5, v9
	v_ashrrev_i32_e32 v11, 31, v10
	v_lshl_add_u64 v[12:13], s[40:41], 0, v[10:11]
	v_lshl_or_b32 v9, v10, 9, v152
	v_mad_u64_u32 v[10:11], s[26:27], v12, s22, v[6:7]
	v_mad_i32_i24 v11, v13, s22, v11
	v_lshl_add_u64 v[10:11], v[10:11], 0, v[4:5]
	v_add_co_u32_e32 v10, vcc, s21, v10
	v_add_u32_e32 v8, 0x700, v8
	s_nop 0
	v_addc_co_u32_e32 v11, vcc, 0, v11, vcc
	v_mov_b32_e32 v10, v210
	v_mov_b32_e32 v11, v211
	v_ashrrev_i32_e32 v8, 5, v8
	v_lshlrev_b32_e32 v14, 16, v10
	v_and_b32_e32 v10, 0xffff0000, v10
	v_lshlrev_b32_e32 v15, 16, v11
	v_mul_f32_e32 v10, 0xbfb8aa3b, v10
	v_mul_f32_e32 v14, 0xbfb8aa3b, v14
	v_exp_f32_e32 v16, v10
	v_mul_f32_e32 v10, 0xbfb8aa3b, v15
	v_exp_f32_e32 v14, v14
	v_exp_f32_e32 v15, v10
	v_and_b32_e32 v11, 0xffff0000, v11
	v_mul_f32_e32 v10, 0xbfb8aa3b, v11
	v_exp_f32_e32 v17, v10
	v_lshlrev_b64 v[10:11], 12, v[12:13]
	v_lshl_add_u64 v[18:19], v[0:1], 0, v[10:11]
	v_lshlrev_b64 v[10:11], 11, v[12:13]
	v_pk_add_f32 v[14:15], v[14:15], 1.0 op_sel_hi:[1,0]
	v_lshl_add_u64 v[20:21], v[2:3], 0, v[10:11]
	ds_read_b128 v[10:13], v9
	v_div_scale_f32 v9, s[26:27], v15, v15, 1.0
	v_rcp_f32_e32 v22, v9
	s_nop 0
	v_fma_f32 v23, -v9, v22, 1.0
	v_fmac_f32_e32 v22, v23, v22
	v_div_scale_f32 v23, vcc, 1.0, v15, 1.0
	v_mul_f32_e32 v24, v23, v22
	v_fma_f32 v25, -v9, v24, v23
	v_fmac_f32_e32 v24, v25, v22
	v_fma_f32 v9, -v9, v24, v23
	v_div_fmas_f32 v9, v9, v22, v24
	v_div_fixup_f32 v23, v9, v15, 1.0
	v_div_scale_f32 v9, s[26:27], v14, v14, 1.0
	v_rcp_f32_e32 v15, v9
	s_nop 0
	v_fma_f32 v22, -v9, v15, 1.0
	v_fmac_f32_e32 v15, v22, v15
	v_div_scale_f32 v22, vcc, 1.0, v14, 1.0
	v_mul_f32_e32 v24, v22, v15
	v_fma_f32 v25, -v9, v24, v22
	v_fmac_f32_e32 v24, v25, v15
	v_fma_f32 v9, -v9, v24, v22
	v_div_fmas_f32 v9, v9, v15, v24
	v_div_fixup_f32 v22, v9, v14, 1.0
	v_pk_add_f32 v[14:15], v[16:17], 1.0 op_sel_hi:[1,0]
	s_waitcnt lgkmcnt(0)
	v_mov_b32_e32 v24, v10
	v_div_scale_f32 v9, s[26:27], v15, v15, 1.0
	v_rcp_f32_e32 v10, v9
	v_mov_b32_e32 v25, v12
	v_fma_f32 v12, -v9, v10, 1.0
	v_fmac_f32_e32 v10, v12, v10
	v_div_scale_f32 v12, vcc, 1.0, v15, 1.0
	v_mul_f32_e32 v16, v12, v10
	v_fma_f32 v17, -v9, v16, v12
	v_fmac_f32_e32 v16, v17, v10
	v_fma_f32 v9, -v9, v16, v12
	v_div_fmas_f32 v9, v9, v10, v16
	v_div_fixup_f32 v27, v9, v15, 1.0
	v_div_scale_f32 v9, s[26:27], v14, v14, 1.0
	v_rcp_f32_e32 v10, v9
	s_nop 0
	v_fma_f32 v12, -v9, v10, 1.0
	v_fmac_f32_e32 v10, v12, v10
	v_div_scale_f32 v12, vcc, 1.0, v14, 1.0
	v_mul_f32_e32 v15, v12, v10
	v_fma_f32 v16, -v9, v15, v12
	v_fmac_f32_e32 v15, v16, v10
	v_fma_f32 v9, -v9, v15, v12
	v_div_fmas_f32 v9, v9, v10, v15
	v_div_fixup_f32 v26, v9, v14, 1.0
	v_mov_b32_e32 v14, v216
	v_mov_b32_e32 v15, v217
	v_mov_b32_e32 v16, v218
	v_mov_b32_e32 v17, v219
	v_mov_b32_e32 v12, v11
	v_mov_b32_e32 v10, v14
	v_mov_b32_e32 v11, v16
	v_pk_fma_f32 v[10:11], v[24:25], v[22:23], v[10:11]
	v_mov_b32_e32 v16, v15
	v_pk_fma_f32 v[12:13], v[12:13], v[26:27], v[16:17]
	v_and_b32_sdwa v9, v11, v95 dst_sel:DWORD dst_unused:UNUSED_PAD src0_sel:WORD_1 src1_sel:DWORD
	v_and_b32_sdwa v14, v10, v95 dst_sel:DWORD dst_unused:UNUSED_PAD src0_sel:WORD_1 src1_sel:DWORD
	v_add3_u32 v10, v10, v14, s39
	v_add3_u32 v9, v11, v9, s39
	v_and_b32_sdwa v11, v13, v95 dst_sel:DWORD dst_unused:UNUSED_PAD src0_sel:WORD_1 src1_sel:DWORD
	v_and_b32_sdwa v14, v12, v95 dst_sel:DWORD dst_unused:UNUSED_PAD src0_sel:WORD_1 src1_sel:DWORD
	v_add3_u32 v11, v13, v11, s39
	v_add3_u32 v12, v12, v14, s39
	v_and_b32_e32 v11, 0xffff0000, v11
	v_and_b32_e32 v12, 0xffff0000, v12
	v_or_b32_sdwa v11, v11, v9 dst_sel:DWORD dst_unused:UNUSED_PAD src0_sel:DWORD src1_sel:WORD_1
	v_or_b32_sdwa v10, v12, v10 dst_sel:DWORD dst_unused:UNUSED_PAD src0_sel:DWORD src1_sel:WORD_1
	v_ashrrev_i32_e32 v9, 31, v8
	global_store_dwordx2 v[20:21], v[10:11], off
	v_lshl_add_u64 v[10:11], s[40:41], 0, v[8:9]
	v_mad_u64_u32 v[6:7], s[26:27], v10, s22, v[6:7]
	v_mad_i32_i24 v7, v11, s22, v7
	v_lshl_add_u64 v[6:7], v[6:7], 0, v[4:5]
	v_add_co_u32_e32 v6, vcc, s21, v6
	v_lshl_or_b32 v8, v8, 9, v152
	s_nop 0
	v_addc_co_u32_e32 v7, vcc, 0, v7, vcc
	v_mov_b32_e32 v6, v220
	v_mov_b32_e32 v7, v221
	v_lshlrev_b32_e32 v9, 16, v6
	v_and_b32_e32 v6, 0xffff0000, v6
	v_lshlrev_b32_e32 v13, 16, v7
	v_mul_f32_e32 v6, 0xbfb8aa3b, v6
	v_mul_f32_e32 v9, 0xbfb8aa3b, v9
	v_exp_f32_e32 v14, v6
	v_mul_f32_e32 v6, 0xbfb8aa3b, v13
	v_exp_f32_e32 v12, v9
	v_exp_f32_e32 v13, v6
	v_and_b32_e32 v7, 0xffff0000, v7
	v_mul_f32_e32 v6, 0xbfb8aa3b, v7
	v_exp_f32_e32 v15, v6
	v_lshlrev_b64 v[6:7], 12, v[10:11]
	v_lshl_add_u64 v[16:17], v[0:1], 0, v[6:7]
	v_lshlrev_b64 v[6:7], 11, v[10:11]
	v_pk_add_f32 v[10:11], v[12:13], 1.0 op_sel_hi:[1,0]
	v_lshl_add_u64 v[18:19], v[2:3], 0, v[6:7]
	v_div_scale_f32 v12, s[26:27], v11, v11, 1.0
	v_rcp_f32_e32 v13, v12
	ds_read_b128 v[6:9], v8
	v_fma_f32 v20, -v12, v13, 1.0
	v_fmac_f32_e32 v13, v20, v13
	v_div_scale_f32 v20, vcc, 1.0, v11, 1.0
	v_mul_f32_e32 v21, v20, v13
	v_fma_f32 v22, -v12, v21, v20
	v_fmac_f32_e32 v21, v22, v13
	v_fma_f32 v12, -v12, v21, v20
	v_div_fmas_f32 v12, v12, v13, v21
	v_div_fixup_f32 v21, v12, v11, 1.0
	v_div_scale_f32 v11, s[26:27], v10, v10, 1.0
	v_rcp_f32_e32 v12, v11
	s_waitcnt lgkmcnt(0)
; DEVI float sigmoidf_(float x) { return 1.f / (1.f + __expf(-x)); }
; DEVI char* wsp(const Params& P, size_t off) { asm volatile("" : "+s"(off)); return P.ws + off; }
; template <int BR, int IN, int OUT>
; DEVI void p6_branch(const Params& P, int pm, int pn, float* macc, char* smem, int tid) {
;     ...
; #pragma unroll 8
;   for (int q = 0; q < 16; ++q) {
;     const int id = tid + 256 * q, row = id >> 5, c4 = id & 31;
;     const long grow = (long)pm * 128 + row;
;     const int gcol = pn * 128 + c4 * 4;
;     float4 a = *reinterpret_cast<const float4*>(T + row * 128 + c4 * 4);
;     float g[4];
;     load4bf(Z + grow * NCOL + (9 + BR) * 1024 + gcol, g);
;     float v[4] = {sigmoidf_(g[0]) * a.x, sigmoidf_(g[1]) * a.y, sigmoidf_(g[2]) * a.z, sigmoidf_(g[3]) * a.w};
;     if (IN == 1) {
;       float mo[4]; load4bf(M + grow * 1024 + gcol, mo);
;       v[0] += mo[0]; v[1] += mo[1]; v[2] += mo[2]; v[3] += mo[3];
;     }
;     if (IN == 2) {
;       float4 mo = *reinterpret_cast<const float4*>(macc + grow * 1024 + gcol);
;       v[0] += mo.x; v[1] += mo.y; v[2] += mo.z; v[3] += mo.w;
;     }
;     if (OUT == 1) *reinterpret_cast<float4*>(macc + grow * 1024 + gcol) = make_float4(v[0], v[1], v[2], v[3]);
;     else store4bf(M + grow * 1024 + gcol, v);
; DEVI void phase6(const Params& P, int l, int pass, char* smem) {
;     ...
;   for (int id = blockIdx.x; id < nM * nN; id += gridDim.x) {
;     int pm, pn; tile_rc_m(id, nM, nN, pm, pn);
;     float* macc = (float*)wsp(P, O_AU);
;     p6_branch<2, 1, 1>(P, pm, pn, macc, smem, tid);
;     p6_branch<1, 2, 0>(P, pm, pn, macc, smem, tid);
;   }
	v_mov_b32_e32 v23, v8
	v_fma_f32 v13, -v11, v12, 1.0
	v_fmac_f32_e32 v12, v13, v12
	v_div_scale_f32 v13, vcc, 1.0, v10, 1.0
	v_mul_f32_e32 v20, v13, v12
	v_fma_f32 v22, -v11, v20, v13
	v_fmac_f32_e32 v20, v22, v12
	v_fma_f32 v11, -v11, v20, v13
	v_div_fmas_f32 v11, v11, v12, v20
	v_div_fixup_f32 v20, v11, v10, 1.0
	v_pk_add_f32 v[10:11], v[14:15], 1.0 op_sel_hi:[1,0]
	v_mov_b32_e32 v22, v6
	v_div_scale_f32 v6, s[26:27], v11, v11, 1.0
	v_rcp_f32_e32 v8, v6
	s_nop 0
	v_fma_f32 v12, -v6, v8, 1.0
	v_fmac_f32_e32 v8, v12, v8
	v_div_scale_f32 v12, vcc, 1.0, v11, 1.0
	v_mul_f32_e32 v13, v12, v8
	v_fma_f32 v14, -v6, v13, v12
	v_fmac_f32_e32 v13, v14, v8
	v_fma_f32 v6, -v6, v13, v12
	v_div_fmas_f32 v6, v6, v8, v13
	v_div_fixup_f32 v15, v6, v11, 1.0
	v_div_scale_f32 v6, s[26:27], v10, v10, 1.0
	v_rcp_f32_e32 v8, v6
	s_nop 0
	v_fma_f32 v11, -v6, v8, 1.0
	v_fmac_f32_e32 v8, v11, v8
	v_div_scale_f32 v11, vcc, 1.0, v10, 1.0
	v_mul_f32_e32 v12, v11, v8
	v_fma_f32 v13, -v6, v12, v11
	v_fmac_f32_e32 v12, v13, v8
	v_fma_f32 v6, -v6, v12, v11
	v_div_fmas_f32 v6, v6, v8, v12
	v_div_fixup_f32 v14, v6, v10, 1.0
	v_mov_b32_e32 v10, v224
	v_mov_b32_e32 v11, v225
	v_mov_b32_e32 v12, v226
	v_mov_b32_e32 v13, v227
	v_mov_b32_e32 v8, v7
	v_mov_b32_e32 v6, v10
	v_mov_b32_e32 v7, v12
	v_pk_fma_f32 v[6:7], v[22:23], v[20:21], v[6:7]
	v_mov_b32_e32 v12, v11
	v_pk_fma_f32 v[8:9], v[8:9], v[14:15], v[12:13]
	v_and_b32_sdwa v10, v7, v95 dst_sel:DWORD dst_unused:UNUSED_PAD src0_sel:WORD_1 src1_sel:DWORD
	v_and_b32_sdwa v11, v6, v95 dst_sel:DWORD dst_unused:UNUSED_PAD src0_sel:WORD_1 src1_sel:DWORD
	v_add3_u32 v6, v6, v11, s39
	v_add3_u32 v7, v7, v10, s39
	v_and_b32_sdwa v10, v9, v95 dst_sel:DWORD dst_unused:UNUSED_PAD src0_sel:WORD_1 src1_sel:DWORD
	v_and_b32_sdwa v11, v8, v95 dst_sel:DWORD dst_unused:UNUSED_PAD src0_sel:WORD_1 src1_sel:DWORD
	v_add3_u32 v9, v9, v10, s39
	v_add3_u32 v8, v8, v11, s39
	v_and_b32_e32 v9, 0xffff0000, v9
	v_and_b32_e32 v8, 0xffff0000, v8
	v_or_b32_sdwa v7, v9, v7 dst_sel:DWORD dst_unused:UNUSED_PAD src0_sel:DWORD src1_sel:WORD_1
	v_or_b32_sdwa v6, v8, v6 dst_sel:DWORD dst_unused:UNUSED_PAD src0_sel:DWORD src1_sel:WORD_1
	global_store_dwordx2 v[18:19], v[6:7], off
	s_cbranch_scc1 .LBB0_741
.Lp6_latch:
	s_add_i32 s2, s2, s23
	s_cmp_lt_i32 s2, s1
	s_cbranch_scc1 .LBB0_730
	v_readlane_b32 vcc_lo, v255, 2
	v_readlane_b32 vcc_hi, v255, 1
	s_nop 0
	s_cmp_eq_u32 vcc_lo, 1
	s_cbranch_scc0 .LBB0_743
	s_cmp_eq_u32 vcc_hi, 0
	s_cbranch_scc0 .LBB0_743
	s_sub_i32 vcc_lo, s2, 0x210
	s_cmp_lt_u32 vcc_lo, 16
	s_cbranch_scc0 .LBB0_743
	v_writelane_b32 v255, 2, 1
	s_add_i32 s2, s2, -16
	s_branch .LBB0_730
